# speedup vs baseline: 1.0371x; 1.0371x over previous
; __device__ __forceinline__ int opaque_tid(int wave_s) { int l; asm volatile("v_mbcnt_lo_u32_b32 %0, -1, 0\n\tv_mbcnt_hi_u32_b32 %0, -1, %0" : "=v"(l)); return (wave_s << 6) | l; }
; #define LAS __attribute__((address_space(3)))
; __device__ __forceinline__ unsigned pk2(float lo, float hi) { return pg8::cvt_pk_bf16(lo, hi); }
; template <int NCH, class RB, class EP>
; __device__ __forceinline__ void tail_gemm(const bf16* A16, const bf16* Bt, int K, int ngroups, int vcu, int G, LAS unsigned char* lds, int wave, RB rb, EP ep) {
;     const int tid = opaque_tid(wave), lane = tid & 63, r = lane & 15, q = lane >> 4;
;     LAS float* red = (LAS float*)lds;
;     const int kw = K >> 3;
; #pragma unroll 1
;     for (int g = vcu; g < ngroups; g += G) {
;         f32x4 acc[NCH];
; #pragma unroll
;         for (int c = 0; c < NCH; ++c) acc[c] = (f32x4){0.f, 0.f, 0.f, 0.f};
;         const bf16* ap = A16 + (size_t)r * K + wave * kw + 8 * q;
; #pragma unroll 2
;         for (int k = 0; k < kw; k += 32) {
; __global__ void __launch_bounds__(NTHR, 2) mk_fwd(Args a_byval) {
;     ...
;                 { bf16* ACT = (bf16*)(ws + WS_ACT);
;                   for (int rep = 0; rep < DUP_TAIL; ++rep)
;                   tail_gemm<2>((const bf16*)(ws + WS_HN) + (size_t)8192 * DM, (const bf16*)(wl + OFF_WGU), DM, DFF / 16, vcu, G, lds, wave0,
;                       [](int g, int ch) { return (g >> 3) * 256 + (g & 7) * 16 + ch * 128; },
;                       [=](int g, int r, int c, const float* v) { const float sg = __builtin_amdgcn_rcpf(1.f + __builtin_amdgcn_exp2f(-v[0] * 1.4426950408889634f));
;                           ACT[(size_t)(8192 + r) * DFF + g * 16 + c] = (bf16)(pk2(v[0] * sg * v[1], 0.f) & 0xffffu); }); }
.LBB0_89:
	s_cmpk_lt_i32 s9, 0x80
	v_mbcnt_lo_u32_b32 v0, -1, 0
	v_mbcnt_hi_u32_b32 v0, -1, v0
	s_cbranch_scc1 .LBB0_96
	v_readlane_b32 s0, v253, 25
	v_lshlrev_b32_e32 v2, 4, v0
	v_and_b32_e32 v2, 0x3f0, v2
	v_or_b32_e32 v1, s0, v0
	v_readlane_b32 s0, v253, 10
	v_lshl_add_u32 v22, v1, 2, 0
	v_readlane_b32 s1, v253, 26
	v_add_u32_e32 v21, s0, v2
	s_movk_i32 s0, 0x100
	v_cmp_gt_i32_e64 s[40:41], s0, v1
	v_ashrrev_i32_e32 v1, 4, v1
	v_bfi_b32 v1, -4, v1, v0
	v_add_u32_e32 v1, 0x2000, v1
	v_mov_b64_e32 v[2:3], s[42:43]
	s_movk_i32 s0, 0x2c00
	v_mad_i64_i32 v[2:3], s[18:19], v1, s0, v[2:3]
	v_lshrrev_b32_e32 v1, 1, v0
	v_readlane_b32 s0, v255, 0
	v_and_b32_e32 v148, 30, v1
	v_readlane_b32 s1, v255, 1
	s_add_u32 s18, s16, s0
	v_and_b32_e32 v20, 15, v0
	s_waitcnt vmcnt(0)
	v_lshl_add_u64 v[8:9], v[2:3], 0, v[148:149]
	v_and_b32_e32 v148, 48, v0
	s_addc_u32 s19, s17, s1
	v_lshl_or_b32 v0, v20, 12, v148
	v_mov_b32_e32 v1, v149
	v_lshl_add_u64 v[12:13], s[18:19], 0, v[148:149]
	v_readlane_b32 s18, v255, 7
	v_lshl_add_u64 v[10:11], s[16:17], 0, v[0:1]
	s_addk_i32 s18, 0xff80
	s_lshl_b32 s5, s18, 5
	s_movk_i32 s7, 0x1000
	s_lshl_b32 s9, s18, 4
	s_movk_i32 s11, 0x800
	v_or_b32_e32 v23, 0x80, v20
	s_branch .LBB0_92
.LBB0_91:
	s_or_b64 exec, exec, s[22:23]
	s_addk_i32 s18, 0x80
	s_add_i32 s5, s5, s7
	s_add_i32 s9, s9, s11
	s_cmpk_gt_i32 s18, 0x15f
	s_barrier
	s_cbranch_scc1 .LBB0_96

; __device__ __forceinline__ unsigned pk2(float lo, float hi) { return pg8::cvt_pk_bf16(lo, hi); }
; __device__ __forceinline__ void phase_mix(KA a, int l, LAS unsigned char* lds, int vcu, int G, int wave) {
;     ...
;     for (int t = gw; t < T_; t += NGW) {
;         const bf16* row = (const bf16*)(a->ws + WS_AO) + (size_t)t * 1024;
;         float v[16]; float ss = 0.f;
;         if (t < 8192) {
;             u32x4 x[2]; x[0] = *(const u32x4*)(row + lane * 8); x[1] = *(const u32x4*)(row + 512 + lane * 8);
; #pragma unroll
;             for (int j = 0; j < 2; ++j) { v[j * 8 + 0] = bflo(x[j].x); v[j * 8 + 1] = bfhi(x[j].x); v[j * 8 + 2] = bflo(x[j].y); v[j * 8 + 3] = bfhi(x[j].y);
;                 v[j * 8 + 4] = bflo(x[j].z); v[j * 8 + 5] = bfhi(x[j].z); v[j * 8 + 6] = bflo(x[j].w); v[j * 8 + 7] = bfhi(x[j].w); }
;         } else {
;             const float* PART = (const float*)(a->ws + WS_PART);
; #pragma unroll
;             for (int j = 0; j < 2; ++j) {
;                 const int h = j * 4 + (lane >> 4), d0 = (lane & 15) * 8, r = t - 8192;
;                 const float* pb = PART + ((size_t)(h * 33) * 16 + r) * 132;
;                 float M = -1e30f;
;                 for (int ck = 0; ck < 33; ++ck) M = fmaxf(M, pb[(size_t)ck * 16 * 132]);
;                 float L = 0.f, o[8] = {0.f, 0.f, 0.f, 0.f, 0.f, 0.f, 0.f, 0.f};
;                 for (int ck = 0; ck < 33; ++ck) { const float* p = pb + (size_t)ck * 16 * 132; const float w = __builtin_amdgcn_exp2f(p[0] - M); L += p[1] * w;
;                     const f32x4 o0 = *(const f32x4*)(p + 4 + d0), o1 = *(const f32x4*)(p + 8 + d0);
;                     o[0] += o0.x * w; o[1] += o0.y * w; o[2] += o0.z * w; o[3] += o0.w * w; o[4] += o1.x * w; o[5] += o1.y * w; o[6] += o1.z * w; o[7] += o1.w * w; }
;                 const float il = 1.0f / L;
; #pragma unroll
;                 for (int e = 0; e < 8; ++e) v[j * 8 + e] = bf2f((unsigned short)(pk2(o[e] * il, 0.f) & 0xffffu));
;             }
;         }
; #pragma unroll
;         for (int e = 0; e < 16; ++e) ss += v[e] * v[e];
;         const float rs = rsqrtf(wave_sum(ss) * (1.0f / 1024) + EPS);
; #pragma unroll
;         for (int j = 0; j < 2; ++j) { const float* g = ga + j * 512 + lane * 8; u32x4 w;
;             w.x = pk2(v[j * 8 + 0] * rs * g[0], v[j * 8 + 1] * rs * g[1]); w.y = pk2(v[j * 8 + 2] * rs * g[2], v[j * 8 + 3] * rs * g[3]);
.LBB0_130:
	s_and_b64 vcc, exec, s[22:23]
	s_cbranch_vccz .LBB0_159
	v_readlane_b32 s0, v254, 62
	s_lshl_b32 s5, s11, 3
	s_lshl_b32 s42, s0, 10
	v_mbcnt_lo_u32_b32 v26, -1, 0
	v_mbcnt_hi_u32_b32 v26, -1, v26
	s_load_dwordx2 s[48:49], s[36:37], 0xa8
	s_add_i32 s44, s5, s81
	s_ashr_i32 s43, s42, 31
	s_add_u32 s40, s16, 0x20c90000
	s_addc_u32 s41, s17, 0
	v_and_b32_e32 v27, 63, v26
	s_cmpk_lt_i32 s44, 0x2010
	v_lshlrev_b32_e32 v148, 5, v27
	s_waitcnt vmcnt(0)
	v_lshlrev_b32_e32 v8, 4, v27
	s_cbranch_scc0 .LBB0_142
	s_load_dwordx2 s[18:19], s[36:37], 0xa0
	s_lshl_b32 s7, s15, 3
	s_add_u32 s52, s16, 0x2f3a0000
	s_addc_u32 s53, s17, 0
	s_lshl_b64 s[20:21], s[42:43], 2
	s_waitcnt lgkmcnt(0)
	s_add_u32 s18, s18, s20
	s_addc_u32 s19, s19, s21
	v_lshrrev_b32_e32 v2, 4, v27
	v_mov_b32_e32 v9, v149
	v_mov_b32_e32 v0, 0x840
	s_movk_i32 s1, 0x210
	v_lshl_add_u64 v[10:11], s[18:19], 0, v[148:149]
	v_mad_u32_u24 v29, v2, s1, v0
	v_lshl_add_u64 v[0:1], s[16:17], 0, v[8:9]
	s_mov_b64 s[18:19], 0x1eb90000
	v_lshl_add_u64 v[14:15], v[0:1], 0, s[18:19]
	v_and_b32_e32 v0, 15, v26
	v_readlane_b32 s0, v254, 43
	v_lshlrev_b32_e32 v0, 5, v0
	v_mov_b32_e32 v1, v149
	s_add_i32 s3, s5, s0
	v_readlane_b32 s0, v254, 44
	v_lshl_add_u64 v[16:17], s[16:17], 0, v[0:1]
	v_mov_b32_e32 v0, s3
	s_add_i32 s3, s5, s0
	v_lshl_add_u64 v[12:13], s[40:41], 0, v[8:9]
	v_mad_u32_u24 v9, v2, s1, v0
	v_mov_b32_e32 v0, s3
	v_mul_u32_u24_e32 v28, 0x210, v2
	v_mad_u32_u24 v30, v2, s1, v0
	global_load_dwordx2 v[232:233], v[10:11], off
	global_load_dwordx2 v[234:235], v[10:11], off offset:8
	global_load_dwordx2 v[236:237], v[10:11], off offset:16
	global_load_dwordx2 v[238:239], v[10:11], off offset:24
	global_load_dwordx2 v[240:241], v[10:11], off offset:2048
	global_load_dwordx2 v[242:243], v[10:11], off offset:2056
	global_load_dwordx2 v[244:245], v[10:11], off offset:2064
	global_load_dwordx2 v[246:247], v[10:11], off offset:2072
	s_branch .LBB0_134
.LBB0_133:
	v_lshlrev_b32_e32 v21, 16, v6
	v_lshlrev_b32_e32 v6, 16, v0
	v_lshlrev_b32_e32 v33, 16, v4
	v_mul_f32_e32 v4, v6, v6
	v_lshlrev_b32_e32 v19, 16, v7
	v_lshlrev_b32_e32 v7, 16, v1
	v_lshlrev_b32_e32 v23, 16, v2
	v_lshlrev_b32_e32 v25, 16, v3
	v_fmac_f32_e32 v4, v36, v36
	v_fmac_f32_e32 v4, v7, v7
	v_fmac_f32_e32 v4, v37, v37
	v_fmac_f32_e32 v4, v23, v23
	v_fmac_f32_e32 v4, v32, v32
	v_fmac_f32_e32 v4, v25, v25
	v_fmac_f32_e32 v4, v31, v31
	v_fmac_f32_e32 v4, v33, v33
	v_lshlrev_b32_e32 v34, 16, v5
	v_fmac_f32_e32 v4, v24, v24
	v_fmac_f32_e32 v4, v34, v34
	v_fmac_f32_e32 v4, v22, v22
	v_pk_mul_f32 v[0:1], v[20:21], v[20:21]
	s_lshl_b64 s[18:19], s[44:45], 12
	v_add_f32_e32 v1, v1, v4
	v_add_f32_e32 v4, v0, v1
	v_pk_mul_f32 v[0:1], v[18:19], v[18:19]
	s_add_i32 s44, s44, s7
	v_add_f32_e32 v1, v1, v4
	v_add_f32_e32 v0, v0, v1
	v_and_b32_e32 v1, 64, v196
	v_add_u32_e32 v1, 64, v1
	v_xor_b32_e32 v4, 1, v196
	v_cmp_lt_i32_e32 vcc, v4, v1
	v_add_u32_e32 v9, s7, v9
	s_cmpk_gt_i32 s44, 0x200f
	v_cndmask_b32_e32 v4, v196, v4, vcc
	v_lshlrev_b32_e32 v4, 2, v4
	ds_bpermute_b32 v4, v4, v0
	v_add_u32_e32 v30, s7, v30
	s_waitcnt lgkmcnt(0)
	v_add_f32_e32 v0, v0, v4
	v_xor_b32_e32 v4, 2, v196
	v_cmp_lt_i32_e32 vcc, v4, v1
	s_nop 1
	v_cndmask_b32_e32 v4, v196, v4, vcc
	v_lshlrev_b32_e32 v4, 2, v4
	ds_bpermute_b32 v4, v4, v0
	s_waitcnt lgkmcnt(0)
	v_add_f32_e32 v0, v0, v4
	v_xor_b32_e32 v4, 4, v196
	v_cmp_lt_i32_e32 vcc, v4, v1
	s_nop 1
	v_cndmask_b32_e32 v4, v196, v4, vcc
	v_lshlrev_b32_e32 v4, 2, v4
	ds_bpermute_b32 v4, v4, v0
	s_waitcnt lgkmcnt(0)
	v_add_f32_e32 v0, v0, v4
	v_xor_b32_e32 v4, 8, v196
	v_cmp_lt_i32_e32 vcc, v4, v1
	s_nop 1
	v_cndmask_b32_e32 v4, v196, v4, vcc
	v_lshlrev_b32_e32 v4, 2, v4
	ds_bpermute_b32 v4, v4, v0
	s_waitcnt lgkmcnt(0)
	v_add_f32_e32 v0, v0, v4
	v_xor_b32_e32 v4, 16, v196
	v_cmp_lt_i32_e32 vcc, v4, v1
	s_nop 1
	v_cndmask_b32_e32 v4, v196, v4, vcc
	v_lshlrev_b32_e32 v4, 2, v4
	ds_bpermute_b32 v4, v4, v0
	s_waitcnt lgkmcnt(0)
	v_add_f32_e32 v0, v0, v4
	v_xor_b32_e32 v4, 32, v196
	v_cmp_lt_i32_e32 vcc, v4, v1
	s_nop 1
	v_cndmask_b32_e32 v1, v196, v4, vcc
	v_lshlrev_b32_e32 v1, 2, v1
	ds_bpermute_b32 v1, v1, v0
	s_waitcnt lgkmcnt(0)
	v_add_f32_e32 v0, v0, v1
	v_fmamk_f32 v0, v0, 0x3a800000, v154
	v_mul_f32_e32 v1, 0x4b800000, v0
	v_cmp_gt_f32_e32 vcc, s54, v0
	s_nop 1
	v_cndmask_b32_e32 v0, v0, v1, vcc
	v_rsq_f32_e32 v0, v0
	s_nop 0
	v_mul_f32_e32 v1, 0x45800000, v0
	v_cndmask_b32_e32 v35, v0, v1, vcc
	v_mul_f32_e32 v0, v35, v6
	v_mul_f32_e32 v1, v35, v36
	v_mul_f32_e32 v0, v232, v0
	v_mul_f32_e32 v1, v233, v1
	v_cvt_pk_bf16_f32 v0, v0, v1
	v_mul_f32_e32 v1, v35, v7
	v_mul_f32_e32 v4, v35, v37
	v_mul_f32_e32 v5, v35, v32
	v_lshl_add_u64 v[6:7], v[12:13], 0, s[18:19]
	v_mul_f32_e32 v18, v35, v18
	v_mul_f32_e32 v1, v234, v1
	v_mul_f32_e32 v2, v235, v4
	v_cvt_pk_bf16_f32 v1, v1, v2
	v_mul_f32_e32 v4, v35, v23
	v_mul_f32_e32 v23, v35, v31
	v_mul_f32_e32 v2, v236, v4
	v_mul_f32_e32 v3, v237, v5
	v_cvt_pk_bf16_f32 v2, v2, v3
	v_mul_f32_e32 v3, v35, v25
	v_mul_f32_e32 v3, v238, v3
	v_mul_f32_e32 v4, v239, v23
	v_cvt_pk_bf16_f32 v3, v3, v4
	global_store_dwordx4 v[6:7], v[0:3], off
	s_nop 1
	v_mul_f32_e32 v4, v35, v22
	v_mul_f32_e32 v2, v35, v33
	v_mul_f32_e32 v3, v35, v24
	v_mul_f32_e32 v5, v35, v20
	v_mul_f32_e32 v0, v240, v2
	v_mul_f32_e32 v1, v241, v3
	v_cvt_pk_bf16_f32 v0, v0, v1
	v_mul_f32_e32 v1, v35, v34
	v_mul_f32_e32 v1, v242, v1
	v_mul_f32_e32 v2, v243, v4
	v_cvt_pk_bf16_f32 v1, v1, v2
	v_mul_f32_e32 v4, v35, v21
	v_mul_f32_e32 v2, v4, v244
	v_mul_f32_e32 v3, v5, v245
	v_cvt_pk_bf16_f32 v2, v2, v3
	v_mul_f32_e32 v3, v35, v19
	v_mul_f32_e32 v3, v3, v246
	v_mul_f32_e32 v4, v18, v247
	v_cvt_pk_bf16_f32 v3, v3, v4
	global_store_dwordx4 v[6:7], v[0:3], off offset:1024
	s_nop 1
	s_cbranch_scc1 .LBB0_142
; __device__ __forceinline__ void phase_mix(KA a, int l, LAS unsigned char* lds, int vcu, int G, int wave) {
;     ...
;             const float* PART = (const float*)(a->ws + WS_PART);
; #pragma unroll
;             for (int j = 0; j < 2; ++j) {
;                 const int h = j * 4 + (lane >> 4), d0 = (lane & 15) * 8, r = t - 8192;
;                 const float* pb = PART + ((size_t)(h * 33) * 16 + r) * 132;
;                 float M = -1e30f;
;                 for (int ck = 0; ck < 33; ++ck) M = fmaxf(M, pb[(size_t)ck * 16 * 132]);
;                 float L = 0.f, o[8] = {0.f, 0.f, 0.f, 0.f, 0.f, 0.f, 0.f, 0.f};
;                 for (int ck = 0; ck < 33; ++ck) { const float* p = pb + (size_t)ck * 16 * 132; const float w = __builtin_amdgcn_exp2f(p[0] - M); L += p[1] * w;
;                     const f32x4 o0 = *(const f32x4*)(p + 4 + d0), o1 = *(const f32x4*)(p + 8 + d0);
;                     o[0] += o0.x * w; o[1] += o0.y * w; o[2] += o0.z * w; o[3] += o0.w * w; o[4] += o1.x * w; o[5] += o1.y * w; o[6] += o1.z * w; o[7] += o1.w * w; }
.LBB0_134:
	s_ashr_i32 s45, s44, 31
	s_cmpk_gt_i32 s44, 0x1fff
	s_mov_b64 s[22:23], -1
	s_cbranch_scc0 .LBB0_140
	s_add_i32 s9, s44, 0xffffe000
	v_and_b32_e32 v150, 15, v26
	v_add_u32_e32 v151, s9, v28
	v_add_u32_e32 v152, s9, v29
	v_lshlrev_b32_e32 v150, 5, v150
	v_mul_u32_u24_e32 v151, 0x210, v151
	v_mul_u32_u24_e32 v152, 0x210, v152
	s_waitcnt vmcnt(0)
	s_mov_b64 s[20:21], s[52:53]
	global_load_dwordx2 v[40:41], v151, s[20:21]
	s_add_u32 s20, s20, 0x2100
	s_addc_u32 s21, s21, 0
	global_load_dwordx2 v[42:43], v151, s[20:21]
	s_add_u32 s20, s20, 0x2100
	s_addc_u32 s21, s21, 0
	global_load_dwordx2 v[44:45], v151, s[20:21]
	s_add_u32 s20, s20, 0x2100
	s_addc_u32 s21, s21, 0
	global_load_dwordx2 v[46:47], v151, s[20:21]
	s_add_u32 s20, s20, 0x2100
	s_addc_u32 s21, s21, 0
	global_load_dwordx2 v[48:49], v151, s[20:21]
	s_add_u32 s20, s20, 0x2100
	s_addc_u32 s21, s21, 0
	global_load_dwordx2 v[50:51], v151, s[20:21]
	s_add_u32 s20, s20, 0x2100
	s_addc_u32 s21, s21, 0
	global_load_dwordx2 v[52:53], v151, s[20:21]
	s_add_u32 s20, s20, 0x2100
	s_addc_u32 s21, s21, 0
	global_load_dwordx2 v[54:55], v151, s[20:21]
	s_add_u32 s20, s20, 0x2100
	s_addc_u32 s21, s21, 0
	global_load_dwordx2 v[56:57], v151, s[20:21]
	s_add_u32 s20, s20, 0x2100
	s_addc_u32 s21, s21, 0
	global_load_dwordx2 v[58:59], v151, s[20:21]
	s_add_u32 s20, s20, 0x2100
	s_addc_u32 s21, s21, 0
	global_load_dwordx2 v[60:61], v151, s[20:21]
	s_add_u32 s20, s20, 0x2100
	s_addc_u32 s21, s21, 0
	global_load_dwordx2 v[62:63], v151, s[20:21]
	s_add_u32 s20, s20, 0x2100
	s_addc_u32 s21, s21, 0
	global_load_dwordx2 v[64:65], v151, s[20:21]
	s_add_u32 s20, s20, 0x2100
	s_addc_u32 s21, s21, 0
	global_load_dwordx2 v[66:67], v151, s[20:21]
	s_add_u32 s20, s20, 0x2100
	s_addc_u32 s21, s21, 0
	global_load_dwordx2 v[68:69], v151, s[20:21]
	s_add_u32 s20, s20, 0x2100
	s_addc_u32 s21, s21, 0
	global_load_dwordx2 v[70:71], v151, s[20:21]
	s_add_u32 s20, s20, 0x2100
	s_addc_u32 s21, s21, 0
	global_load_dwordx2 v[72:73], v151, s[20:21]
	s_add_u32 s20, s20, 0x2100
	s_addc_u32 s21, s21, 0
	global_load_dwordx2 v[74:75], v151, s[20:21]
	s_add_u32 s20, s20, 0x2100
	s_addc_u32 s21, s21, 0
	global_load_dwordx2 v[76:77], v151, s[20:21]
	s_add_u32 s20, s20, 0x2100
	s_addc_u32 s21, s21, 0
	global_load_dwordx2 v[78:79], v151, s[20:21]
	s_add_u32 s20, s20, 0x2100
	s_addc_u32 s21, s21, 0
	global_load_dwordx2 v[80:81], v151, s[20:21]
	s_add_u32 s20, s20, 0x2100
	s_addc_u32 s21, s21, 0
	global_load_dwordx2 v[82:83], v151, s[20:21]
	s_add_u32 s20, s20, 0x2100
	s_addc_u32 s21, s21, 0
	global_load_dwordx2 v[84:85], v151, s[20:21]
	s_add_u32 s20, s20, 0x2100
	s_addc_u32 s21, s21, 0
	global_load_dwordx2 v[86:87], v151, s[20:21]
	s_add_u32 s20, s20, 0x2100
	s_addc_u32 s21, s21, 0
	global_load_dwordx2 v[88:89], v151, s[20:21]
	s_add_u32 s20, s20, 0x2100
	s_addc_u32 s21, s21, 0
	global_load_dwordx2 v[90:91], v151, s[20:21]
	s_add_u32 s20, s20, 0x2100
	s_addc_u32 s21, s21, 0
	global_load_dwordx2 v[92:93], v151, s[20:21]
	s_add_u32 s20, s20, 0x2100
	s_addc_u32 s21, s21, 0
	global_load_dwordx2 v[94:95], v151, s[20:21]
	s_add_u32 s20, s20, 0x2100
	s_addc_u32 s21, s21, 0
	global_load_dwordx2 v[96:97], v151, s[20:21]
	s_add_u32 s20, s20, 0x2100
	s_addc_u32 s21, s21, 0
	global_load_dwordx2 v[98:99], v151, s[20:21]
	s_add_u32 s20, s20, 0x2100
	s_addc_u32 s21, s21, 0
	global_load_dwordx2 v[100:101], v151, s[20:21]
	s_add_u32 s20, s20, 0x2100
	s_addc_u32 s21, s21, 0
	global_load_dwordx2 v[102:103], v151, s[20:21]
	s_add_u32 s20, s20, 0x2100
	s_addc_u32 s21, s21, 0
	global_load_dwordx2 v[104:105], v151, s[20:21]
	v_add_u32_e32 v153, v151, v150
	s_mov_b64 s[20:21], s[52:53]
	global_load_dwordx4 v[114:117], v153, s[20:21] offset:16
	global_load_dwordx4 v[118:121], v153, s[20:21] offset:32
	s_add_u32 s20, s20, 0x2100
	s_addc_u32 s21, s21, 0
	global_load_dwordx4 v[122:125], v153, s[20:21] offset:16
	global_load_dwordx4 v[126:129], v153, s[20:21] offset:32
	s_add_u32 s20, s20, 0x2100
	s_addc_u32 s21, s21, 0
	global_load_dwordx4 v[130:133], v153, s[20:21] offset:16
	global_load_dwordx4 v[134:137], v153, s[20:21] offset:32
	s_add_u32 s20, s20, 0x2100
	s_addc_u32 s21, s21, 0
	global_load_dwordx4 v[138:141], v153, s[20:21] offset:16
	global_load_dwordx4 v[142:145], v153, s[20:21] offset:32
	s_add_u32 s20, s20, 0x2100
	s_addc_u32 s21, s21, 0
	global_load_dwordx4 v[156:159], v153, s[20:21] offset:16
	global_load_dwordx4 v[160:163], v153, s[20:21] offset:32
	s_add_u32 s20, s20, 0x2100
	s_addc_u32 s21, s21, 0
	global_load_dwordx4 v[164:167], v153, s[20:21] offset:16
	global_load_dwordx4 v[168:171], v153, s[20:21] offset:32
	s_add_u32 s20, s20, 0x2100
	s_addc_u32 s21, s21, 0
	global_load_dwordx4 v[172:175], v153, s[20:21] offset:16
	global_load_dwordx4 v[176:179], v153, s[20:21] offset:32
	s_add_u32 s20, s20, 0x2100
	s_addc_u32 s21, s21, 0
	global_load_dwordx4 v[180:183], v153, s[20:21] offset:16
	global_load_dwordx4 v[184:187], v153, s[20:21] offset:32
	s_add_u32 s20, s20, 0x2100
	s_addc_u32 s21, s21, 0
	global_load_dwordx4 v[208:211], v153, s[20:21] offset:16
	global_load_dwordx4 v[212:215], v153, s[20:21] offset:32
	s_add_u32 s20, s20, 0x2100
	s_addc_u32 s21, s21, 0
	global_load_dwordx4 v[216:219], v153, s[20:21] offset:16
	global_load_dwordx4 v[220:223], v153, s[20:21] offset:32
	s_add_u32 s20, s20, 0x2100
	s_addc_u32 s21, s21, 0
	global_load_dwordx4 v[224:227], v153, s[20:21] offset:16
	global_load_dwordx4 v[228:231], v153, s[20:21] offset:32
	s_add_u32 s20, s20, 0x2100
	s_addc_u32 s21, s21, 0
	s_waitcnt vmcnt(22)
; __device__ __forceinline__ void phase_mix(KA a, int l, LAS unsigned char* lds, int vcu, int G, int wave) {
;     ...
;                 float M = -1e30f;
;                 for (int ck = 0; ck < 33; ++ck) M = fmaxf(M, pb[(size_t)ck * 16 * 132]);
;                 float L = 0.f, o[8] = {0.f, 0.f, 0.f, 0.f, 0.f, 0.f, 0.f, 0.f};
;                 for (int ck = 0; ck < 33; ++ck) { const float* p = pb + (size_t)ck * 16 * 132; const float w = __builtin_amdgcn_exp2f(p[0] - M); L += p[1] * w;
;                     const f32x4 o0 = *(const f32x4*)(p + 4 + d0), o1 = *(const f32x4*)(p + 8 + d0);
;                     o[0] += o0.x * w; o[1] += o0.y * w; o[2] += o0.z * w; o[3] += o0.w * w; o[4] += o1.x * w; o[5] += o1.y * w; o[6] += o1.z * w; o[7] += o1.w * w; }
;                 const float il = 1.0f / L;
	v_mov_b32_e32 v194, 0xf149f2ca
	v_max3_f32 v194, v194, v40, v42
	v_max3_f32 v194, v194, v44, v46
	v_max3_f32 v194, v194, v48, v50
	v_max3_f32 v194, v194, v52, v54
	v_max3_f32 v194, v194, v56, v58
	v_max3_f32 v194, v194, v60, v62
	v_max3_f32 v194, v194, v64, v66
	v_max3_f32 v194, v194, v68, v70
	v_max3_f32 v194, v194, v72, v74
	v_max3_f32 v194, v194, v76, v78
	v_max3_f32 v194, v194, v80, v82
	v_max3_f32 v194, v194, v84, v86
	v_max3_f32 v194, v194, v88, v90
	v_max3_f32 v194, v194, v92, v94
	v_max3_f32 v194, v194, v96, v98
	v_max3_f32 v194, v194, v100, v102
	v_max_f32_e32 v194, v194, v104
	v_mov_b32_e32 v195, 0
	v_sub_f32_e32 v40, v40, v194
	v_sub_f32_e32 v42, v42, v194
	v_sub_f32_e32 v44, v44, v194
	v_sub_f32_e32 v46, v46, v194
	v_sub_f32_e32 v48, v48, v194
	v_sub_f32_e32 v50, v50, v194
	v_sub_f32_e32 v52, v52, v194
	v_sub_f32_e32 v54, v54, v194
	v_sub_f32_e32 v56, v56, v194
	v_sub_f32_e32 v58, v58, v194
	v_sub_f32_e32 v60, v60, v194
	v_sub_f32_e32 v62, v62, v194
	v_sub_f32_e32 v64, v64, v194
	v_sub_f32_e32 v66, v66, v194
	v_sub_f32_e32 v68, v68, v194
	v_sub_f32_e32 v70, v70, v194
	v_sub_f32_e32 v72, v72, v194
	v_sub_f32_e32 v74, v74, v194
	v_sub_f32_e32 v76, v76, v194
	v_sub_f32_e32 v78, v78, v194
	v_sub_f32_e32 v80, v80, v194
	v_sub_f32_e32 v82, v82, v194
	v_sub_f32_e32 v84, v84, v194
	v_sub_f32_e32 v86, v86, v194
	v_sub_f32_e32 v88, v88, v194
	v_sub_f32_e32 v90, v90, v194
	v_sub_f32_e32 v92, v92, v194
	v_sub_f32_e32 v94, v94, v194
	v_sub_f32_e32 v96, v96, v194
	v_sub_f32_e32 v98, v98, v194
	v_sub_f32_e32 v100, v100, v194
	v_sub_f32_e32 v102, v102, v194
	v_sub_f32_e32 v104, v104, v194
	v_exp_f32_e32 v40, v40
	v_exp_f32_e32 v42, v42
	v_exp_f32_e32 v44, v44
	v_exp_f32_e32 v46, v46
	v_exp_f32_e32 v48, v48
	v_exp_f32_e32 v50, v50
	v_exp_f32_e32 v52, v52
	v_exp_f32_e32 v54, v54
	v_exp_f32_e32 v56, v56
	v_exp_f32_e32 v58, v58
	v_exp_f32_e32 v60, v60
	v_exp_f32_e32 v62, v62
	v_exp_f32_e32 v64, v64
	v_exp_f32_e32 v66, v66
	v_exp_f32_e32 v68, v68
	v_exp_f32_e32 v70, v70
	v_exp_f32_e32 v72, v72
	v_exp_f32_e32 v74, v74
	v_exp_f32_e32 v76, v76
	v_exp_f32_e32 v78, v78
	v_exp_f32_e32 v80, v80
	v_exp_f32_e32 v82, v82
	v_exp_f32_e32 v84, v84
	v_exp_f32_e32 v86, v86
	v_exp_f32_e32 v88, v88
	v_exp_f32_e32 v90, v90
	v_exp_f32_e32 v92, v92
	v_exp_f32_e32 v94, v94
	v_exp_f32_e32 v96, v96
	v_exp_f32_e32 v98, v98
	v_exp_f32_e32 v100, v100
	v_exp_f32_e32 v102, v102
	v_exp_f32_e32 v104, v104
	s_nop 0
	v_fmac_f32_e32 v195, v41, v40
	v_fmac_f32_e32 v195, v43, v42
	v_fmac_f32_e32 v195, v45, v44
	v_fmac_f32_e32 v195, v47, v46
	v_fmac_f32_e32 v195, v49, v48
	v_fmac_f32_e32 v195, v51, v50
	v_fmac_f32_e32 v195, v53, v52
	v_fmac_f32_e32 v195, v55, v54
	v_fmac_f32_e32 v195, v57, v56
	v_fmac_f32_e32 v195, v59, v58
	v_fmac_f32_e32 v195, v61, v60
	v_fmac_f32_e32 v195, v63, v62
	v_fmac_f32_e32 v195, v65, v64
	v_fmac_f32_e32 v195, v67, v66
	v_fmac_f32_e32 v195, v69, v68
	v_fmac_f32_e32 v195, v71, v70
	v_fmac_f32_e32 v195, v73, v72
	v_fmac_f32_e32 v195, v75, v74
	v_fmac_f32_e32 v195, v77, v76
	v_fmac_f32_e32 v195, v79, v78
	v_fmac_f32_e32 v195, v81, v80
	v_fmac_f32_e32 v195, v83, v82
	v_fmac_f32_e32 v195, v85, v84
	v_fmac_f32_e32 v195, v87, v86
	v_fmac_f32_e32 v195, v89, v88
	v_fmac_f32_e32 v195, v91, v90
	v_fmac_f32_e32 v195, v93, v92
	v_fmac_f32_e32 v195, v95, v94
	v_fmac_f32_e32 v195, v97, v96
	v_fmac_f32_e32 v195, v99, v98
	v_fmac_f32_e32 v195, v101, v100
	v_fmac_f32_e32 v195, v103, v102
	v_fmac_f32_e32 v195, v105, v104
	v_mov_b32_e32 v106, 0
	v_mov_b32_e32 v107, 0
	v_mov_b32_e32 v108, 0
	v_mov_b32_e32 v109, 0
	v_mov_b32_e32 v110, 0
	v_mov_b32_e32 v111, 0
	v_mov_b32_e32 v112, 0
	v_mov_b32_e32 v113, 0
	s_waitcnt vmcnt(0)
	v_pk_fma_f32 v[106:107], v[40:41], v[114:115], v[106:107] op_sel_hi:[0,1,1]
	v_pk_fma_f32 v[108:109], v[40:41], v[116:117], v[108:109] op_sel_hi:[0,1,1]
	v_pk_fma_f32 v[110:111], v[40:41], v[118:119], v[110:111] op_sel_hi:[0,1,1]
	v_pk_fma_f32 v[112:113], v[40:41], v[120:121], v[112:113] op_sel_hi:[0,1,1]
	v_pk_fma_f32 v[106:107], v[42:43], v[122:123], v[106:107] op_sel_hi:[0,1,1]
	v_pk_fma_f32 v[108:109], v[42:43], v[124:125], v[108:109] op_sel_hi:[0,1,1]
	v_pk_fma_f32 v[110:111], v[42:43], v[126:127], v[110:111] op_sel_hi:[0,1,1]
	v_pk_fma_f32 v[112:113], v[42:43], v[128:129], v[112:113] op_sel_hi:[0,1,1]
	v_pk_fma_f32 v[106:107], v[44:45], v[130:131], v[106:107] op_sel_hi:[0,1,1]
	v_pk_fma_f32 v[108:109], v[44:45], v[132:133], v[108:109] op_sel_hi:[0,1,1]
	v_pk_fma_f32 v[110:111], v[44:45], v[134:135], v[110:111] op_sel_hi:[0,1,1]
	v_pk_fma_f32 v[112:113], v[44:45], v[136:137], v[112:113] op_sel_hi:[0,1,1]
	v_pk_fma_f32 v[106:107], v[46:47], v[138:139], v[106:107] op_sel_hi:[0,1,1]
	v_pk_fma_f32 v[108:109], v[46:47], v[140:141], v[108:109] op_sel_hi:[0,1,1]
	v_pk_fma_f32 v[110:111], v[46:47], v[142:143], v[110:111] op_sel_hi:[0,1,1]
	v_pk_fma_f32 v[112:113], v[46:47], v[144:145], v[112:113] op_sel_hi:[0,1,1]
	v_pk_fma_f32 v[106:107], v[48:49], v[156:157], v[106:107] op_sel_hi:[0,1,1]
	v_pk_fma_f32 v[108:109], v[48:49], v[158:159], v[108:109] op_sel_hi:[0,1,1]
	v_pk_fma_f32 v[110:111], v[48:49], v[160:161], v[110:111] op_sel_hi:[0,1,1]
	v_pk_fma_f32 v[112:113], v[48:49], v[162:163], v[112:113] op_sel_hi:[0,1,1]
	v_pk_fma_f32 v[106:107], v[50:51], v[164:165], v[106:107] op_sel_hi:[0,1,1]
	v_pk_fma_f32 v[108:109], v[50:51], v[166:167], v[108:109] op_sel_hi:[0,1,1]
	v_pk_fma_f32 v[110:111], v[50:51], v[168:169], v[110:111] op_sel_hi:[0,1,1]
	v_pk_fma_f32 v[112:113], v[50:51], v[170:171], v[112:113] op_sel_hi:[0,1,1]
	v_pk_fma_f32 v[106:107], v[52:53], v[172:173], v[106:107] op_sel_hi:[0,1,1]
	v_pk_fma_f32 v[108:109], v[52:53], v[174:175], v[108:109] op_sel_hi:[0,1,1]
; __device__ __forceinline__ void phase_mix(KA a, int l, LAS unsigned char* lds, int vcu, int G, int wave) {
;     ...
;                 for (int ck = 0; ck < 33; ++ck) { const float* p = pb + (size_t)ck * 16 * 132; const float w = __builtin_amdgcn_exp2f(p[0] - M); L += p[1] * w;
;                     const f32x4 o0 = *(const f32x4*)(p + 4 + d0), o1 = *(const f32x4*)(p + 8 + d0);
;                     o[0] += o0.x * w; o[1] += o0.y * w; o[2] += o0.z * w; o[3] += o0.w * w; o[4] += o1.x * w; o[5] += o1.y * w; o[6] += o1.z * w; o[7] += o1.w * w; }
	v_pk_fma_f32 v[110:111], v[52:53], v[176:177], v[110:111] op_sel_hi:[0,1,1]
	v_pk_fma_f32 v[112:113], v[52:53], v[178:179], v[112:113] op_sel_hi:[0,1,1]
	v_pk_fma_f32 v[106:107], v[54:55], v[180:181], v[106:107] op_sel_hi:[0,1,1]
	v_pk_fma_f32 v[108:109], v[54:55], v[182:183], v[108:109] op_sel_hi:[0,1,1]
	v_pk_fma_f32 v[110:111], v[54:55], v[184:185], v[110:111] op_sel_hi:[0,1,1]
	v_pk_fma_f32 v[112:113], v[54:55], v[186:187], v[112:113] op_sel_hi:[0,1,1]
	v_pk_fma_f32 v[106:107], v[56:57], v[208:209], v[106:107] op_sel_hi:[0,1,1]
	v_pk_fma_f32 v[108:109], v[56:57], v[210:211], v[108:109] op_sel_hi:[0,1,1]
	v_pk_fma_f32 v[110:111], v[56:57], v[212:213], v[110:111] op_sel_hi:[0,1,1]
	v_pk_fma_f32 v[112:113], v[56:57], v[214:215], v[112:113] op_sel_hi:[0,1,1]
	v_pk_fma_f32 v[106:107], v[58:59], v[216:217], v[106:107] op_sel_hi:[0,1,1]
	v_pk_fma_f32 v[108:109], v[58:59], v[218:219], v[108:109] op_sel_hi:[0,1,1]
	v_pk_fma_f32 v[110:111], v[58:59], v[220:221], v[110:111] op_sel_hi:[0,1,1]
	v_pk_fma_f32 v[112:113], v[58:59], v[222:223], v[112:113] op_sel_hi:[0,1,1]
	v_pk_fma_f32 v[106:107], v[60:61], v[224:225], v[106:107] op_sel_hi:[0,1,1]
	v_pk_fma_f32 v[108:109], v[60:61], v[226:227], v[108:109] op_sel_hi:[0,1,1]
	v_pk_fma_f32 v[110:111], v[60:61], v[228:229], v[110:111] op_sel_hi:[0,1,1]
	v_pk_fma_f32 v[112:113], v[60:61], v[230:231], v[112:113] op_sel_hi:[0,1,1]
	s_nop 1
	global_load_dwordx4 v[114:117], v153, s[20:21] offset:16
	global_load_dwordx4 v[118:121], v153, s[20:21] offset:32
	s_add_u32 s20, s20, 0x2100
	s_addc_u32 s21, s21, 0
	global_load_dwordx4 v[122:125], v153, s[20:21] offset:16
	global_load_dwordx4 v[126:129], v153, s[20:21] offset:32
	s_add_u32 s20, s20, 0x2100
	s_addc_u32 s21, s21, 0
	global_load_dwordx4 v[130:133], v153, s[20:21] offset:16
	global_load_dwordx4 v[134:137], v153, s[20:21] offset:32
	s_add_u32 s20, s20, 0x2100
	s_addc_u32 s21, s21, 0
	global_load_dwordx4 v[138:141], v153, s[20:21] offset:16
	global_load_dwordx4 v[142:145], v153, s[20:21] offset:32
	s_add_u32 s20, s20, 0x2100
	s_addc_u32 s21, s21, 0
	global_load_dwordx4 v[156:159], v153, s[20:21] offset:16
	global_load_dwordx4 v[160:163], v153, s[20:21] offset:32
	s_add_u32 s20, s20, 0x2100
	s_addc_u32 s21, s21, 0
	global_load_dwordx4 v[164:167], v153, s[20:21] offset:16
	global_load_dwordx4 v[168:171], v153, s[20:21] offset:32
	s_add_u32 s20, s20, 0x2100
	s_addc_u32 s21, s21, 0
	global_load_dwordx4 v[172:175], v153, s[20:21] offset:16
	global_load_dwordx4 v[176:179], v153, s[20:21] offset:32
	s_add_u32 s20, s20, 0x2100
	s_addc_u32 s21, s21, 0
	global_load_dwordx4 v[180:183], v153, s[20:21] offset:16
	global_load_dwordx4 v[184:187], v153, s[20:21] offset:32
	s_add_u32 s20, s20, 0x2100
	s_addc_u32 s21, s21, 0
	global_load_dwordx4 v[208:211], v153, s[20:21] offset:16
	global_load_dwordx4 v[212:215], v153, s[20:21] offset:32
	s_add_u32 s20, s20, 0x2100
	s_addc_u32 s21, s21, 0
	global_load_dwordx4 v[216:219], v153, s[20:21] offset:16
	global_load_dwordx4 v[220:223], v153, s[20:21] offset:32
	s_add_u32 s20, s20, 0x2100
	s_addc_u32 s21, s21, 0
	global_load_dwordx4 v[224:227], v153, s[20:21] offset:16
	global_load_dwordx4 v[228:231], v153, s[20:21] offset:32
	s_add_u32 s20, s20, 0x2100
	s_addc_u32 s21, s21, 0
	s_waitcnt vmcnt(0)
	v_pk_fma_f32 v[106:107], v[62:63], v[114:115], v[106:107] op_sel_hi:[0,1,1]
	v_pk_fma_f32 v[108:109], v[62:63], v[116:117], v[108:109] op_sel_hi:[0,1,1]
	v_pk_fma_f32 v[110:111], v[62:63], v[118:119], v[110:111] op_sel_hi:[0,1,1]
	v_pk_fma_f32 v[112:113], v[62:63], v[120:121], v[112:113] op_sel_hi:[0,1,1]
	v_pk_fma_f32 v[106:107], v[64:65], v[122:123], v[106:107] op_sel_hi:[0,1,1]
	v_pk_fma_f32 v[108:109], v[64:65], v[124:125], v[108:109] op_sel_hi:[0,1,1]
	v_pk_fma_f32 v[110:111], v[64:65], v[126:127], v[110:111] op_sel_hi:[0,1,1]
	v_pk_fma_f32 v[112:113], v[64:65], v[128:129], v[112:113] op_sel_hi:[0,1,1]
	v_pk_fma_f32 v[106:107], v[66:67], v[130:131], v[106:107] op_sel_hi:[0,1,1]
	v_pk_fma_f32 v[108:109], v[66:67], v[132:133], v[108:109] op_sel_hi:[0,1,1]
	v_pk_fma_f32 v[110:111], v[66:67], v[134:135], v[110:111] op_sel_hi:[0,1,1]
	v_pk_fma_f32 v[112:113], v[66:67], v[136:137], v[112:113] op_sel_hi:[0,1,1]
	v_pk_fma_f32 v[106:107], v[68:69], v[138:139], v[106:107] op_sel_hi:[0,1,1]
	v_pk_fma_f32 v[108:109], v[68:69], v[140:141], v[108:109] op_sel_hi:[0,1,1]
	v_pk_fma_f32 v[110:111], v[68:69], v[142:143], v[110:111] op_sel_hi:[0,1,1]
	v_pk_fma_f32 v[112:113], v[68:69], v[144:145], v[112:113] op_sel_hi:[0,1,1]
	v_pk_fma_f32 v[106:107], v[70:71], v[156:157], v[106:107] op_sel_hi:[0,1,1]
	v_pk_fma_f32 v[108:109], v[70:71], v[158:159], v[108:109] op_sel_hi:[0,1,1]
	v_pk_fma_f32 v[110:111], v[70:71], v[160:161], v[110:111] op_sel_hi:[0,1,1]
	v_pk_fma_f32 v[112:113], v[70:71], v[162:163], v[112:113] op_sel_hi:[0,1,1]
	v_pk_fma_f32 v[106:107], v[72:73], v[164:165], v[106:107] op_sel_hi:[0,1,1]
	v_pk_fma_f32 v[108:109], v[72:73], v[166:167], v[108:109] op_sel_hi:[0,1,1]
	v_pk_fma_f32 v[110:111], v[72:73], v[168:169], v[110:111] op_sel_hi:[0,1,1]
	v_pk_fma_f32 v[112:113], v[72:73], v[170:171], v[112:113] op_sel_hi:[0,1,1]
	v_pk_fma_f32 v[106:107], v[74:75], v[172:173], v[106:107] op_sel_hi:[0,1,1]
	v_pk_fma_f32 v[108:109], v[74:75], v[174:175], v[108:109] op_sel_hi:[0,1,1]
	v_pk_fma_f32 v[110:111], v[74:75], v[176:177], v[110:111] op_sel_hi:[0,1,1]
	v_pk_fma_f32 v[112:113], v[74:75], v[178:179], v[112:113] op_sel_hi:[0,1,1]
	v_pk_fma_f32 v[106:107], v[76:77], v[180:181], v[106:107] op_sel_hi:[0,1,1]
	v_pk_fma_f32 v[108:109], v[76:77], v[182:183], v[108:109] op_sel_hi:[0,1,1]
	v_pk_fma_f32 v[110:111], v[76:77], v[184:185], v[110:111] op_sel_hi:[0,1,1]
; __device__ __forceinline__ void phase_mix(KA a, int l, LAS unsigned char* lds, int vcu, int G, int wave) {
;     ...
;                 for (int ck = 0; ck < 33; ++ck) { const float* p = pb + (size_t)ck * 16 * 132; const float w = __builtin_amdgcn_exp2f(p[0] - M); L += p[1] * w;
;                     const f32x4 o0 = *(const f32x4*)(p + 4 + d0), o1 = *(const f32x4*)(p + 8 + d0);
;                     o[0] += o0.x * w; o[1] += o0.y * w; o[2] += o0.z * w; o[3] += o0.w * w; o[4] += o1.x * w; o[5] += o1.y * w; o[6] += o1.z * w; o[7] += o1.w * w; }
	v_pk_fma_f32 v[112:113], v[76:77], v[186:187], v[112:113] op_sel_hi:[0,1,1]
	v_pk_fma_f32 v[106:107], v[78:79], v[208:209], v[106:107] op_sel_hi:[0,1,1]
	v_pk_fma_f32 v[108:109], v[78:79], v[210:211], v[108:109] op_sel_hi:[0,1,1]
	v_pk_fma_f32 v[110:111], v[78:79], v[212:213], v[110:111] op_sel_hi:[0,1,1]
	v_pk_fma_f32 v[112:113], v[78:79], v[214:215], v[112:113] op_sel_hi:[0,1,1]
	v_pk_fma_f32 v[106:107], v[80:81], v[216:217], v[106:107] op_sel_hi:[0,1,1]
	v_pk_fma_f32 v[108:109], v[80:81], v[218:219], v[108:109] op_sel_hi:[0,1,1]
	v_pk_fma_f32 v[110:111], v[80:81], v[220:221], v[110:111] op_sel_hi:[0,1,1]
	v_pk_fma_f32 v[112:113], v[80:81], v[222:223], v[112:113] op_sel_hi:[0,1,1]
	v_pk_fma_f32 v[106:107], v[82:83], v[224:225], v[106:107] op_sel_hi:[0,1,1]
	v_pk_fma_f32 v[108:109], v[82:83], v[226:227], v[108:109] op_sel_hi:[0,1,1]
	v_pk_fma_f32 v[110:111], v[82:83], v[228:229], v[110:111] op_sel_hi:[0,1,1]
	v_pk_fma_f32 v[112:113], v[82:83], v[230:231], v[112:113] op_sel_hi:[0,1,1]
	s_nop 1
	global_load_dwordx4 v[114:117], v153, s[20:21] offset:16
	global_load_dwordx4 v[118:121], v153, s[20:21] offset:32
	s_add_u32 s20, s20, 0x2100
	s_addc_u32 s21, s21, 0
	global_load_dwordx4 v[122:125], v153, s[20:21] offset:16
	global_load_dwordx4 v[126:129], v153, s[20:21] offset:32
	s_add_u32 s20, s20, 0x2100
	s_addc_u32 s21, s21, 0
	global_load_dwordx4 v[130:133], v153, s[20:21] offset:16
	global_load_dwordx4 v[134:137], v153, s[20:21] offset:32
	s_add_u32 s20, s20, 0x2100
	s_addc_u32 s21, s21, 0
	global_load_dwordx4 v[138:141], v153, s[20:21] offset:16
	global_load_dwordx4 v[142:145], v153, s[20:21] offset:32
	s_add_u32 s20, s20, 0x2100
	s_addc_u32 s21, s21, 0
	global_load_dwordx4 v[156:159], v153, s[20:21] offset:16
	global_load_dwordx4 v[160:163], v153, s[20:21] offset:32
	s_add_u32 s20, s20, 0x2100
	s_addc_u32 s21, s21, 0
	global_load_dwordx4 v[164:167], v153, s[20:21] offset:16
	global_load_dwordx4 v[168:171], v153, s[20:21] offset:32
	s_add_u32 s20, s20, 0x2100
	s_addc_u32 s21, s21, 0
	global_load_dwordx4 v[172:175], v153, s[20:21] offset:16
	global_load_dwordx4 v[176:179], v153, s[20:21] offset:32
	s_add_u32 s20, s20, 0x2100
	s_addc_u32 s21, s21, 0
	global_load_dwordx4 v[180:183], v153, s[20:21] offset:16
	global_load_dwordx4 v[184:187], v153, s[20:21] offset:32
	s_add_u32 s20, s20, 0x2100
	s_addc_u32 s21, s21, 0
	global_load_dwordx4 v[208:211], v153, s[20:21] offset:16
	global_load_dwordx4 v[212:215], v153, s[20:21] offset:32
	s_add_u32 s20, s20, 0x2100
	s_addc_u32 s21, s21, 0
	global_load_dwordx4 v[216:219], v153, s[20:21] offset:16
	global_load_dwordx4 v[220:223], v153, s[20:21] offset:32
	s_add_u32 s20, s20, 0x2100
	s_addc_u32 s21, s21, 0
	global_load_dwordx4 v[224:227], v153, s[20:21] offset:16
	global_load_dwordx4 v[228:231], v153, s[20:21] offset:32
	s_waitcnt vmcnt(0)
	v_pk_fma_f32 v[106:107], v[84:85], v[114:115], v[106:107] op_sel_hi:[0,1,1]
	v_pk_fma_f32 v[108:109], v[84:85], v[116:117], v[108:109] op_sel_hi:[0,1,1]
	v_pk_fma_f32 v[110:111], v[84:85], v[118:119], v[110:111] op_sel_hi:[0,1,1]
	v_pk_fma_f32 v[112:113], v[84:85], v[120:121], v[112:113] op_sel_hi:[0,1,1]
	v_pk_fma_f32 v[106:107], v[86:87], v[122:123], v[106:107] op_sel_hi:[0,1,1]
	v_pk_fma_f32 v[108:109], v[86:87], v[124:125], v[108:109] op_sel_hi:[0,1,1]
	v_pk_fma_f32 v[110:111], v[86:87], v[126:127], v[110:111] op_sel_hi:[0,1,1]
	v_pk_fma_f32 v[112:113], v[86:87], v[128:129], v[112:113] op_sel_hi:[0,1,1]
	v_pk_fma_f32 v[106:107], v[88:89], v[130:131], v[106:107] op_sel_hi:[0,1,1]
	v_pk_fma_f32 v[108:109], v[88:89], v[132:133], v[108:109] op_sel_hi:[0,1,1]
	v_pk_fma_f32 v[110:111], v[88:89], v[134:135], v[110:111] op_sel_hi:[0,1,1]
	v_pk_fma_f32 v[112:113], v[88:89], v[136:137], v[112:113] op_sel_hi:[0,1,1]
	v_pk_fma_f32 v[106:107], v[90:91], v[138:139], v[106:107] op_sel_hi:[0,1,1]
	v_pk_fma_f32 v[108:109], v[90:91], v[140:141], v[108:109] op_sel_hi:[0,1,1]
	v_pk_fma_f32 v[110:111], v[90:91], v[142:143], v[110:111] op_sel_hi:[0,1,1]
	v_pk_fma_f32 v[112:113], v[90:91], v[144:145], v[112:113] op_sel_hi:[0,1,1]
	v_pk_fma_f32 v[106:107], v[92:93], v[156:157], v[106:107] op_sel_hi:[0,1,1]
	v_pk_fma_f32 v[108:109], v[92:93], v[158:159], v[108:109] op_sel_hi:[0,1,1]
	v_pk_fma_f32 v[110:111], v[92:93], v[160:161], v[110:111] op_sel_hi:[0,1,1]
	v_pk_fma_f32 v[112:113], v[92:93], v[162:163], v[112:113] op_sel_hi:[0,1,1]
	v_pk_fma_f32 v[106:107], v[94:95], v[164:165], v[106:107] op_sel_hi:[0,1,1]
	v_pk_fma_f32 v[108:109], v[94:95], v[166:167], v[108:109] op_sel_hi:[0,1,1]
	v_pk_fma_f32 v[110:111], v[94:95], v[168:169], v[110:111] op_sel_hi:[0,1,1]
	v_pk_fma_f32 v[112:113], v[94:95], v[170:171], v[112:113] op_sel_hi:[0,1,1]
	v_pk_fma_f32 v[106:107], v[96:97], v[172:173], v[106:107] op_sel_hi:[0,1,1]
	v_pk_fma_f32 v[108:109], v[96:97], v[174:175], v[108:109] op_sel_hi:[0,1,1]
	v_pk_fma_f32 v[110:111], v[96:97], v[176:177], v[110:111] op_sel_hi:[0,1,1]
	v_pk_fma_f32 v[112:113], v[96:97], v[178:179], v[112:113] op_sel_hi:[0,1,1]
	v_pk_fma_f32 v[106:107], v[98:99], v[180:181], v[106:107] op_sel_hi:[0,1,1]
	v_pk_fma_f32 v[108:109], v[98:99], v[182:183], v[108:109] op_sel_hi:[0,1,1]
	v_pk_fma_f32 v[110:111], v[98:99], v[184:185], v[110:111] op_sel_hi:[0,1,1]
	v_pk_fma_f32 v[112:113], v[98:99], v[186:187], v[112:113] op_sel_hi:[0,1,1]
	v_pk_fma_f32 v[106:107], v[100:101], v[208:209], v[106:107] op_sel_hi:[0,1,1]
	v_pk_fma_f32 v[108:109], v[100:101], v[210:211], v[108:109] op_sel_hi:[0,1,1]
	v_pk_fma_f32 v[110:111], v[100:101], v[212:213], v[110:111] op_sel_hi:[0,1,1]
	v_pk_fma_f32 v[112:113], v[100:101], v[214:215], v[112:113] op_sel_hi:[0,1,1]
; __device__ __forceinline__ unsigned pk2(float lo, float hi) { return pg8::cvt_pk_bf16(lo, hi); }
; __device__ __forceinline__ float bf2f(unsigned short u) { return __uint_as_float((unsigned)u << 16); }
; __device__ __forceinline__ void phase_mix(KA a, int l, LAS unsigned char* lds, int vcu, int G, int wave) {
;     ...
;                 for (int ck = 0; ck < 33; ++ck) { const float* p = pb + (size_t)ck * 16 * 132; const float w = __builtin_amdgcn_exp2f(p[0] - M); L += p[1] * w;
;                     const f32x4 o0 = *(const f32x4*)(p + 4 + d0), o1 = *(const f32x4*)(p + 8 + d0);
;                     o[0] += o0.x * w; o[1] += o0.y * w; o[2] += o0.z * w; o[3] += o0.w * w; o[4] += o1.x * w; o[5] += o1.y * w; o[6] += o1.z * w; o[7] += o1.w * w; }
;                 const float il = 1.0f / L;
; #pragma unroll
;                 for (int e = 0; e < 8; ++e) v[j * 8 + e] = bf2f((unsigned short)(pk2(o[e] * il, 0.f) & 0xffffu));
;             }
	v_pk_fma_f32 v[106:107], v[102:103], v[216:217], v[106:107] op_sel_hi:[0,1,1]
	v_pk_fma_f32 v[108:109], v[102:103], v[218:219], v[108:109] op_sel_hi:[0,1,1]
	v_pk_fma_f32 v[110:111], v[102:103], v[220:221], v[110:111] op_sel_hi:[0,1,1]
	v_pk_fma_f32 v[112:113], v[102:103], v[222:223], v[112:113] op_sel_hi:[0,1,1]
	v_pk_fma_f32 v[106:107], v[104:105], v[224:225], v[106:107] op_sel_hi:[0,1,1]
	v_pk_fma_f32 v[108:109], v[104:105], v[226:227], v[108:109] op_sel_hi:[0,1,1]
	v_pk_fma_f32 v[110:111], v[104:105], v[228:229], v[110:111] op_sel_hi:[0,1,1]
	v_pk_fma_f32 v[112:113], v[104:105], v[230:231], v[112:113] op_sel_hi:[0,1,1]
	v_div_scale_f32 v194, s[18:19], v195, v195, 1.0
	v_rcp_f32_e32 v197, v194
	s_nop 0
	v_fma_f32 v40, -v194, v197, 1.0
	v_fmac_f32_e32 v197, v40, v197
	v_div_scale_f32 v40, vcc, 1.0, v195, 1.0
	v_mul_f32_e32 v41, v40, v197
	v_fma_f32 v42, -v194, v41, v40
	v_fmac_f32_e32 v41, v42, v197
	v_fma_f32 v194, -v194, v41, v40
	v_div_fmas_f32 v194, v194, v197, v41
	v_div_fixup_f32 v194, v194, v195, 1.0
	v_mul_f32_e32 v40, v194, v106
	v_mul_f32_e32 v41, v194, v107
	v_cvt_pk_bf16_f32 v0, v40, v149
	v_cvt_pk_bf16_f32 v36, v41, v149
	s_nop 0
	v_lshlrev_b32_e32 v36, 16, v36
	v_mul_f32_e32 v40, v194, v108
	v_mul_f32_e32 v41, v194, v109
	v_cvt_pk_bf16_f32 v1, v40, v149
	v_cvt_pk_bf16_f32 v37, v41, v149
	s_nop 0
	v_lshlrev_b32_e32 v37, 16, v37
	v_mul_f32_e32 v40, v194, v110
	v_mul_f32_e32 v41, v194, v111
	v_cvt_pk_bf16_f32 v2, v40, v149
	v_cvt_pk_bf16_f32 v32, v41, v149
	s_nop 0
	v_lshlrev_b32_e32 v32, 16, v32
	v_mul_f32_e32 v40, v194, v112
	v_mul_f32_e32 v41, v194, v113
	v_cvt_pk_bf16_f32 v3, v40, v149
	v_cvt_pk_bf16_f32 v31, v41, v149
	s_nop 0
	v_lshlrev_b32_e32 v31, 16, v31
	s_mov_b64 s[20:21], s[52:53]
	global_load_dwordx2 v[40:41], v152, s[20:21]
	s_add_u32 s20, s20, 0x2100
	s_addc_u32 s21, s21, 0
	global_load_dwordx2 v[42:43], v152, s[20:21]
	s_add_u32 s20, s20, 0x2100
	s_addc_u32 s21, s21, 0
	global_load_dwordx2 v[44:45], v152, s[20:21]
	s_add_u32 s20, s20, 0x2100
	s_addc_u32 s21, s21, 0
	global_load_dwordx2 v[46:47], v152, s[20:21]
	s_add_u32 s20, s20, 0x2100
	s_addc_u32 s21, s21, 0
	global_load_dwordx2 v[48:49], v152, s[20:21]
	s_add_u32 s20, s20, 0x2100
	s_addc_u32 s21, s21, 0
	global_load_dwordx2 v[50:51], v152, s[20:21]
	s_add_u32 s20, s20, 0x2100
	s_addc_u32 s21, s21, 0
	global_load_dwordx2 v[52:53], v152, s[20:21]
	s_add_u32 s20, s20, 0x2100
	s_addc_u32 s21, s21, 0
	global_load_dwordx2 v[54:55], v152, s[20:21]
	s_add_u32 s20, s20, 0x2100
	s_addc_u32 s21, s21, 0
	global_load_dwordx2 v[56:57], v152, s[20:21]
	s_add_u32 s20, s20, 0x2100
	s_addc_u32 s21, s21, 0
	global_load_dwordx2 v[58:59], v152, s[20:21]
	s_add_u32 s20, s20, 0x2100
	s_addc_u32 s21, s21, 0
	global_load_dwordx2 v[60:61], v152, s[20:21]
	s_add_u32 s20, s20, 0x2100
	s_addc_u32 s21, s21, 0
	global_load_dwordx2 v[62:63], v152, s[20:21]
	s_add_u32 s20, s20, 0x2100
	s_addc_u32 s21, s21, 0
	global_load_dwordx2 v[64:65], v152, s[20:21]
	s_add_u32 s20, s20, 0x2100
	s_addc_u32 s21, s21, 0
	global_load_dwordx2 v[66:67], v152, s[20:21]
	s_add_u32 s20, s20, 0x2100
	s_addc_u32 s21, s21, 0
	global_load_dwordx2 v[68:69], v152, s[20:21]
	s_add_u32 s20, s20, 0x2100
	s_addc_u32 s21, s21, 0
	global_load_dwordx2 v[70:71], v152, s[20:21]
	s_add_u32 s20, s20, 0x2100
	s_addc_u32 s21, s21, 0
	global_load_dwordx2 v[72:73], v152, s[20:21]
	s_add_u32 s20, s20, 0x2100
	s_addc_u32 s21, s21, 0
	global_load_dwordx2 v[74:75], v152, s[20:21]
	s_add_u32 s20, s20, 0x2100
	s_addc_u32 s21, s21, 0
	global_load_dwordx2 v[76:77], v152, s[20:21]
	s_add_u32 s20, s20, 0x2100
	s_addc_u32 s21, s21, 0
	global_load_dwordx2 v[78:79], v152, s[20:21]
	s_add_u32 s20, s20, 0x2100
	s_addc_u32 s21, s21, 0
	global_load_dwordx2 v[80:81], v152, s[20:21]
	s_add_u32 s20, s20, 0x2100
	s_addc_u32 s21, s21, 0
	global_load_dwordx2 v[82:83], v152, s[20:21]
	s_add_u32 s20, s20, 0x2100
	s_addc_u32 s21, s21, 0
	global_load_dwordx2 v[84:85], v152, s[20:21]
	s_add_u32 s20, s20, 0x2100
	s_addc_u32 s21, s21, 0
	global_load_dwordx2 v[86:87], v152, s[20:21]
	s_add_u32 s20, s20, 0x2100
	s_addc_u32 s21, s21, 0
	global_load_dwordx2 v[88:89], v152, s[20:21]
	s_add_u32 s20, s20, 0x2100
	s_addc_u32 s21, s21, 0
	global_load_dwordx2 v[90:91], v152, s[20:21]
	s_add_u32 s20, s20, 0x2100
	s_addc_u32 s21, s21, 0
	global_load_dwordx2 v[92:93], v152, s[20:21]
	s_add_u32 s20, s20, 0x2100
	s_addc_u32 s21, s21, 0
	global_load_dwordx2 v[94:95], v152, s[20:21]
	s_add_u32 s20, s20, 0x2100
	s_addc_u32 s21, s21, 0
	global_load_dwordx2 v[96:97], v152, s[20:21]
	s_add_u32 s20, s20, 0x2100
	s_addc_u32 s21, s21, 0
	global_load_dwordx2 v[98:99], v152, s[20:21]
	s_add_u32 s20, s20, 0x2100
	s_addc_u32 s21, s21, 0
	global_load_dwordx2 v[100:101], v152, s[20:21]
	s_add_u32 s20, s20, 0x2100
	s_addc_u32 s21, s21, 0
	global_load_dwordx2 v[102:103], v152, s[20:21]
	s_add_u32 s20, s20, 0x2100
	s_addc_u32 s21, s21, 0
	global_load_dwordx2 v[104:105], v152, s[20:21]
	v_add_u32_e32 v153, v152, v150
	s_mov_b64 s[20:21], s[52:53]
	global_load_dwordx4 v[114:117], v153, s[20:21] offset:16
	global_load_dwordx4 v[118:121], v153, s[20:21] offset:32
	s_add_u32 s20, s20, 0x2100
	s_addc_u32 s21, s21, 0
	global_load_dwordx4 v[122:125], v153, s[20:21] offset:16
	global_load_dwordx4 v[126:129], v153, s[20:21] offset:32
	s_add_u32 s20, s20, 0x2100
	s_addc_u32 s21, s21, 0
	global_load_dwordx4 v[130:133], v153, s[20:21] offset:16
	global_load_dwordx4 v[134:137], v153, s[20:21] offset:32
	s_add_u32 s20, s20, 0x2100
	s_addc_u32 s21, s21, 0
	global_load_dwordx4 v[138:141], v153, s[20:21] offset:16
	global_load_dwordx4 v[142:145], v153, s[20:21] offset:32
	s_add_u32 s20, s20, 0x2100
	s_addc_u32 s21, s21, 0
	global_load_dwordx4 v[156:159], v153, s[20:21] offset:16
	global_load_dwordx4 v[160:163], v153, s[20:21] offset:32
	s_add_u32 s20, s20, 0x2100
	s_addc_u32 s21, s21, 0
	global_load_dwordx4 v[164:167], v153, s[20:21] offset:16
	global_load_dwordx4 v[168:171], v153, s[20:21] offset:32
	s_add_u32 s20, s20, 0x2100
	s_addc_u32 s21, s21, 0
	global_load_dwordx4 v[172:175], v153, s[20:21] offset:16
	global_load_dwordx4 v[176:179], v153, s[20:21] offset:32
	s_add_u32 s20, s20, 0x2100
	s_addc_u32 s21, s21, 0
	global_load_dwordx4 v[180:183], v153, s[20:21] offset:16
	global_load_dwordx4 v[184:187], v153, s[20:21] offset:32
	s_add_u32 s20, s20, 0x2100
	s_addc_u32 s21, s21, 0
	global_load_dwordx4 v[208:211], v153, s[20:21] offset:16
	global_load_dwordx4 v[212:215], v153, s[20:21] offset:32
	s_add_u32 s20, s20, 0x2100
	s_addc_u32 s21, s21, 0
	global_load_dwordx4 v[216:219], v153, s[20:21] offset:16
	global_load_dwordx4 v[220:223], v153, s[20:21] offset:32
	s_add_u32 s20, s20, 0x2100
	s_addc_u32 s21, s21, 0
	global_load_dwordx4 v[224:227], v153, s[20:21] offset:16
	global_load_dwordx4 v[228:231], v153, s[20:21] offset:32
	s_add_u32 s20, s20, 0x2100
	s_addc_u32 s21, s21, 0
	s_waitcnt vmcnt(22)
; __device__ __forceinline__ void phase_mix(KA a, int l, LAS unsigned char* lds, int vcu, int G, int wave) {
;     ...
;                 const int h = j * 4 + (lane >> 4), d0 = (lane & 15) * 8, r = t - 8192;
;                 const float* pb = PART + ((size_t)(h * 33) * 16 + r) * 132;
;                 float M = -1e30f;
;                 for (int ck = 0; ck < 33; ++ck) M = fmaxf(M, pb[(size_t)ck * 16 * 132]);
;                 float L = 0.f, o[8] = {0.f, 0.f, 0.f, 0.f, 0.f, 0.f, 0.f, 0.f};
;                 for (int ck = 0; ck < 33; ++ck) { const float* p = pb + (size_t)ck * 16 * 132; const float w = __builtin_amdgcn_exp2f(p[0] - M); L += p[1] * w;
;                     const f32x4 o0 = *(const f32x4*)(p + 4 + d0), o1 = *(const f32x4*)(p + 8 + d0);
;                     o[0] += o0.x * w; o[1] += o0.y * w; o[2] += o0.z * w; o[3] += o0.w * w; o[4] += o1.x * w; o[5] += o1.y * w; o[6] += o1.z * w; o[7] += o1.w * w; }
	v_mov_b32_e32 v194, 0xf149f2ca
	v_max3_f32 v194, v194, v40, v42
	v_max3_f32 v194, v194, v44, v46
	v_max3_f32 v194, v194, v48, v50
	v_max3_f32 v194, v194, v52, v54
	v_max3_f32 v194, v194, v56, v58
	v_max3_f32 v194, v194, v60, v62
	v_max3_f32 v194, v194, v64, v66
	v_max3_f32 v194, v194, v68, v70
	v_max3_f32 v194, v194, v72, v74
	v_max3_f32 v194, v194, v76, v78
	v_max3_f32 v194, v194, v80, v82
	v_max3_f32 v194, v194, v84, v86
	v_max3_f32 v194, v194, v88, v90
	v_max3_f32 v194, v194, v92, v94
	v_max3_f32 v194, v194, v96, v98
	v_max3_f32 v194, v194, v100, v102
	v_max_f32_e32 v194, v194, v104
	v_mov_b32_e32 v195, 0
	v_sub_f32_e32 v40, v40, v194
	v_sub_f32_e32 v42, v42, v194
	v_sub_f32_e32 v44, v44, v194
	v_sub_f32_e32 v46, v46, v194
	v_sub_f32_e32 v48, v48, v194
	v_sub_f32_e32 v50, v50, v194
	v_sub_f32_e32 v52, v52, v194
	v_sub_f32_e32 v54, v54, v194
	v_sub_f32_e32 v56, v56, v194
	v_sub_f32_e32 v58, v58, v194
	v_sub_f32_e32 v60, v60, v194
	v_sub_f32_e32 v62, v62, v194
	v_sub_f32_e32 v64, v64, v194
	v_sub_f32_e32 v66, v66, v194
	v_sub_f32_e32 v68, v68, v194
	v_sub_f32_e32 v70, v70, v194
	v_sub_f32_e32 v72, v72, v194
	v_sub_f32_e32 v74, v74, v194
	v_sub_f32_e32 v76, v76, v194
	v_sub_f32_e32 v78, v78, v194
	v_sub_f32_e32 v80, v80, v194
	v_sub_f32_e32 v82, v82, v194
	v_sub_f32_e32 v84, v84, v194
	v_sub_f32_e32 v86, v86, v194
	v_sub_f32_e32 v88, v88, v194
	v_sub_f32_e32 v90, v90, v194
	v_sub_f32_e32 v92, v92, v194
	v_sub_f32_e32 v94, v94, v194
	v_sub_f32_e32 v96, v96, v194
	v_sub_f32_e32 v98, v98, v194
	v_sub_f32_e32 v100, v100, v194
	v_sub_f32_e32 v102, v102, v194
	v_sub_f32_e32 v104, v104, v194
	v_exp_f32_e32 v40, v40
	v_exp_f32_e32 v42, v42
	v_exp_f32_e32 v44, v44
	v_exp_f32_e32 v46, v46
	v_exp_f32_e32 v48, v48
	v_exp_f32_e32 v50, v50
	v_exp_f32_e32 v52, v52
	v_exp_f32_e32 v54, v54
	v_exp_f32_e32 v56, v56
	v_exp_f32_e32 v58, v58
	v_exp_f32_e32 v60, v60
	v_exp_f32_e32 v62, v62
	v_exp_f32_e32 v64, v64
	v_exp_f32_e32 v66, v66
	v_exp_f32_e32 v68, v68
	v_exp_f32_e32 v70, v70
	v_exp_f32_e32 v72, v72
	v_exp_f32_e32 v74, v74
	v_exp_f32_e32 v76, v76
	v_exp_f32_e32 v78, v78
	v_exp_f32_e32 v80, v80
	v_exp_f32_e32 v82, v82
	v_exp_f32_e32 v84, v84
	v_exp_f32_e32 v86, v86
	v_exp_f32_e32 v88, v88
	v_exp_f32_e32 v90, v90
	v_exp_f32_e32 v92, v92
	v_exp_f32_e32 v94, v94
	v_exp_f32_e32 v96, v96
	v_exp_f32_e32 v98, v98
	v_exp_f32_e32 v100, v100
	v_exp_f32_e32 v102, v102
	v_exp_f32_e32 v104, v104
	s_nop 0
	v_fmac_f32_e32 v195, v41, v40
	v_fmac_f32_e32 v195, v43, v42
	v_fmac_f32_e32 v195, v45, v44
	v_fmac_f32_e32 v195, v47, v46
	v_fmac_f32_e32 v195, v49, v48
	v_fmac_f32_e32 v195, v51, v50
	v_fmac_f32_e32 v195, v53, v52
	v_fmac_f32_e32 v195, v55, v54
	v_fmac_f32_e32 v195, v57, v56
	v_fmac_f32_e32 v195, v59, v58
	v_fmac_f32_e32 v195, v61, v60
	v_fmac_f32_e32 v195, v63, v62
	v_fmac_f32_e32 v195, v65, v64
	v_fmac_f32_e32 v195, v67, v66
	v_fmac_f32_e32 v195, v69, v68
	v_fmac_f32_e32 v195, v71, v70
	v_fmac_f32_e32 v195, v73, v72
	v_fmac_f32_e32 v195, v75, v74
	v_fmac_f32_e32 v195, v77, v76
	v_fmac_f32_e32 v195, v79, v78
	v_fmac_f32_e32 v195, v81, v80
	v_fmac_f32_e32 v195, v83, v82
	v_fmac_f32_e32 v195, v85, v84
	v_fmac_f32_e32 v195, v87, v86
	v_fmac_f32_e32 v195, v89, v88
	v_fmac_f32_e32 v195, v91, v90
	v_fmac_f32_e32 v195, v93, v92
	v_fmac_f32_e32 v195, v95, v94
	v_fmac_f32_e32 v195, v97, v96
	v_fmac_f32_e32 v195, v99, v98
	v_fmac_f32_e32 v195, v101, v100
	v_fmac_f32_e32 v195, v103, v102
	v_fmac_f32_e32 v195, v105, v104
	v_mov_b32_e32 v106, 0
	v_mov_b32_e32 v107, 0
	v_mov_b32_e32 v108, 0
	v_mov_b32_e32 v109, 0
	v_mov_b32_e32 v110, 0
	v_mov_b32_e32 v111, 0
	v_mov_b32_e32 v112, 0
	v_mov_b32_e32 v113, 0
	s_waitcnt vmcnt(0)
	v_pk_fma_f32 v[106:107], v[40:41], v[114:115], v[106:107] op_sel_hi:[0,1,1]
	v_pk_fma_f32 v[108:109], v[40:41], v[116:117], v[108:109] op_sel_hi:[0,1,1]
	v_pk_fma_f32 v[110:111], v[40:41], v[118:119], v[110:111] op_sel_hi:[0,1,1]
	v_pk_fma_f32 v[112:113], v[40:41], v[120:121], v[112:113] op_sel_hi:[0,1,1]
	v_pk_fma_f32 v[106:107], v[42:43], v[122:123], v[106:107] op_sel_hi:[0,1,1]
	v_pk_fma_f32 v[108:109], v[42:43], v[124:125], v[108:109] op_sel_hi:[0,1,1]
	v_pk_fma_f32 v[110:111], v[42:43], v[126:127], v[110:111] op_sel_hi:[0,1,1]
	v_pk_fma_f32 v[112:113], v[42:43], v[128:129], v[112:113] op_sel_hi:[0,1,1]
	v_pk_fma_f32 v[106:107], v[44:45], v[130:131], v[106:107] op_sel_hi:[0,1,1]
	v_pk_fma_f32 v[108:109], v[44:45], v[132:133], v[108:109] op_sel_hi:[0,1,1]
	v_pk_fma_f32 v[110:111], v[44:45], v[134:135], v[110:111] op_sel_hi:[0,1,1]
	v_pk_fma_f32 v[112:113], v[44:45], v[136:137], v[112:113] op_sel_hi:[0,1,1]
	v_pk_fma_f32 v[106:107], v[46:47], v[138:139], v[106:107] op_sel_hi:[0,1,1]
	v_pk_fma_f32 v[108:109], v[46:47], v[140:141], v[108:109] op_sel_hi:[0,1,1]
	v_pk_fma_f32 v[110:111], v[46:47], v[142:143], v[110:111] op_sel_hi:[0,1,1]
	v_pk_fma_f32 v[112:113], v[46:47], v[144:145], v[112:113] op_sel_hi:[0,1,1]
	v_pk_fma_f32 v[106:107], v[48:49], v[156:157], v[106:107] op_sel_hi:[0,1,1]
	v_pk_fma_f32 v[108:109], v[48:49], v[158:159], v[108:109] op_sel_hi:[0,1,1]
	v_pk_fma_f32 v[110:111], v[48:49], v[160:161], v[110:111] op_sel_hi:[0,1,1]
	v_pk_fma_f32 v[112:113], v[48:49], v[162:163], v[112:113] op_sel_hi:[0,1,1]
	v_pk_fma_f32 v[106:107], v[50:51], v[164:165], v[106:107] op_sel_hi:[0,1,1]
	v_pk_fma_f32 v[108:109], v[50:51], v[166:167], v[108:109] op_sel_hi:[0,1,1]
	v_pk_fma_f32 v[110:111], v[50:51], v[168:169], v[110:111] op_sel_hi:[0,1,1]
	v_pk_fma_f32 v[112:113], v[50:51], v[170:171], v[112:113] op_sel_hi:[0,1,1]
	v_pk_fma_f32 v[106:107], v[52:53], v[172:173], v[106:107] op_sel_hi:[0,1,1]
	v_pk_fma_f32 v[108:109], v[52:53], v[174:175], v[108:109] op_sel_hi:[0,1,1]
; __device__ __forceinline__ void phase_mix(KA a, int l, LAS unsigned char* lds, int vcu, int G, int wave) {
;     ...
;                 for (int ck = 0; ck < 33; ++ck) { const float* p = pb + (size_t)ck * 16 * 132; const float w = __builtin_amdgcn_exp2f(p[0] - M); L += p[1] * w;
;                     const f32x4 o0 = *(const f32x4*)(p + 4 + d0), o1 = *(const f32x4*)(p + 8 + d0);
;                     o[0] += o0.x * w; o[1] += o0.y * w; o[2] += o0.z * w; o[3] += o0.w * w; o[4] += o1.x * w; o[5] += o1.y * w; o[6] += o1.z * w; o[7] += o1.w * w; }
	v_pk_fma_f32 v[110:111], v[52:53], v[176:177], v[110:111] op_sel_hi:[0,1,1]
	v_pk_fma_f32 v[112:113], v[52:53], v[178:179], v[112:113] op_sel_hi:[0,1,1]
	v_pk_fma_f32 v[106:107], v[54:55], v[180:181], v[106:107] op_sel_hi:[0,1,1]
	v_pk_fma_f32 v[108:109], v[54:55], v[182:183], v[108:109] op_sel_hi:[0,1,1]
	v_pk_fma_f32 v[110:111], v[54:55], v[184:185], v[110:111] op_sel_hi:[0,1,1]
	v_pk_fma_f32 v[112:113], v[54:55], v[186:187], v[112:113] op_sel_hi:[0,1,1]
	v_pk_fma_f32 v[106:107], v[56:57], v[208:209], v[106:107] op_sel_hi:[0,1,1]
	v_pk_fma_f32 v[108:109], v[56:57], v[210:211], v[108:109] op_sel_hi:[0,1,1]
	v_pk_fma_f32 v[110:111], v[56:57], v[212:213], v[110:111] op_sel_hi:[0,1,1]
	v_pk_fma_f32 v[112:113], v[56:57], v[214:215], v[112:113] op_sel_hi:[0,1,1]
	v_pk_fma_f32 v[106:107], v[58:59], v[216:217], v[106:107] op_sel_hi:[0,1,1]
	v_pk_fma_f32 v[108:109], v[58:59], v[218:219], v[108:109] op_sel_hi:[0,1,1]
	v_pk_fma_f32 v[110:111], v[58:59], v[220:221], v[110:111] op_sel_hi:[0,1,1]
	v_pk_fma_f32 v[112:113], v[58:59], v[222:223], v[112:113] op_sel_hi:[0,1,1]
	v_pk_fma_f32 v[106:107], v[60:61], v[224:225], v[106:107] op_sel_hi:[0,1,1]
	v_pk_fma_f32 v[108:109], v[60:61], v[226:227], v[108:109] op_sel_hi:[0,1,1]
	v_pk_fma_f32 v[110:111], v[60:61], v[228:229], v[110:111] op_sel_hi:[0,1,1]
	v_pk_fma_f32 v[112:113], v[60:61], v[230:231], v[112:113] op_sel_hi:[0,1,1]
	s_nop 1
	global_load_dwordx4 v[114:117], v153, s[20:21] offset:16
	global_load_dwordx4 v[118:121], v153, s[20:21] offset:32
	s_add_u32 s20, s20, 0x2100
	s_addc_u32 s21, s21, 0
	global_load_dwordx4 v[122:125], v153, s[20:21] offset:16
	global_load_dwordx4 v[126:129], v153, s[20:21] offset:32
	s_add_u32 s20, s20, 0x2100
	s_addc_u32 s21, s21, 0
	global_load_dwordx4 v[130:133], v153, s[20:21] offset:16
	global_load_dwordx4 v[134:137], v153, s[20:21] offset:32
	s_add_u32 s20, s20, 0x2100
	s_addc_u32 s21, s21, 0
	global_load_dwordx4 v[138:141], v153, s[20:21] offset:16
	global_load_dwordx4 v[142:145], v153, s[20:21] offset:32
	s_add_u32 s20, s20, 0x2100
	s_addc_u32 s21, s21, 0
	global_load_dwordx4 v[156:159], v153, s[20:21] offset:16
	global_load_dwordx4 v[160:163], v153, s[20:21] offset:32
	s_add_u32 s20, s20, 0x2100
	s_addc_u32 s21, s21, 0
	global_load_dwordx4 v[164:167], v153, s[20:21] offset:16
	global_load_dwordx4 v[168:171], v153, s[20:21] offset:32
	s_add_u32 s20, s20, 0x2100
	s_addc_u32 s21, s21, 0
	global_load_dwordx4 v[172:175], v153, s[20:21] offset:16
	global_load_dwordx4 v[176:179], v153, s[20:21] offset:32
	s_add_u32 s20, s20, 0x2100
	s_addc_u32 s21, s21, 0
	global_load_dwordx4 v[180:183], v153, s[20:21] offset:16
	global_load_dwordx4 v[184:187], v153, s[20:21] offset:32
	s_add_u32 s20, s20, 0x2100
	s_addc_u32 s21, s21, 0
	global_load_dwordx4 v[208:211], v153, s[20:21] offset:16
	global_load_dwordx4 v[212:215], v153, s[20:21] offset:32
	s_add_u32 s20, s20, 0x2100
	s_addc_u32 s21, s21, 0
	global_load_dwordx4 v[216:219], v153, s[20:21] offset:16
	global_load_dwordx4 v[220:223], v153, s[20:21] offset:32
	s_add_u32 s20, s20, 0x2100
	s_addc_u32 s21, s21, 0
	global_load_dwordx4 v[224:227], v153, s[20:21] offset:16
	global_load_dwordx4 v[228:231], v153, s[20:21] offset:32
	s_add_u32 s20, s20, 0x2100
	s_addc_u32 s21, s21, 0
	s_waitcnt vmcnt(0)
	v_pk_fma_f32 v[106:107], v[62:63], v[114:115], v[106:107] op_sel_hi:[0,1,1]
	v_pk_fma_f32 v[108:109], v[62:63], v[116:117], v[108:109] op_sel_hi:[0,1,1]
	v_pk_fma_f32 v[110:111], v[62:63], v[118:119], v[110:111] op_sel_hi:[0,1,1]
	v_pk_fma_f32 v[112:113], v[62:63], v[120:121], v[112:113] op_sel_hi:[0,1,1]
	v_pk_fma_f32 v[106:107], v[64:65], v[122:123], v[106:107] op_sel_hi:[0,1,1]
	v_pk_fma_f32 v[108:109], v[64:65], v[124:125], v[108:109] op_sel_hi:[0,1,1]
	v_pk_fma_f32 v[110:111], v[64:65], v[126:127], v[110:111] op_sel_hi:[0,1,1]
	v_pk_fma_f32 v[112:113], v[64:65], v[128:129], v[112:113] op_sel_hi:[0,1,1]
	v_pk_fma_f32 v[106:107], v[66:67], v[130:131], v[106:107] op_sel_hi:[0,1,1]
	v_pk_fma_f32 v[108:109], v[66:67], v[132:133], v[108:109] op_sel_hi:[0,1,1]
	v_pk_fma_f32 v[110:111], v[66:67], v[134:135], v[110:111] op_sel_hi:[0,1,1]
	v_pk_fma_f32 v[112:113], v[66:67], v[136:137], v[112:113] op_sel_hi:[0,1,1]
	v_pk_fma_f32 v[106:107], v[68:69], v[138:139], v[106:107] op_sel_hi:[0,1,1]
	v_pk_fma_f32 v[108:109], v[68:69], v[140:141], v[108:109] op_sel_hi:[0,1,1]
	v_pk_fma_f32 v[110:111], v[68:69], v[142:143], v[110:111] op_sel_hi:[0,1,1]
	v_pk_fma_f32 v[112:113], v[68:69], v[144:145], v[112:113] op_sel_hi:[0,1,1]
	v_pk_fma_f32 v[106:107], v[70:71], v[156:157], v[106:107] op_sel_hi:[0,1,1]
	v_pk_fma_f32 v[108:109], v[70:71], v[158:159], v[108:109] op_sel_hi:[0,1,1]
	v_pk_fma_f32 v[110:111], v[70:71], v[160:161], v[110:111] op_sel_hi:[0,1,1]
	v_pk_fma_f32 v[112:113], v[70:71], v[162:163], v[112:113] op_sel_hi:[0,1,1]
	v_pk_fma_f32 v[106:107], v[72:73], v[164:165], v[106:107] op_sel_hi:[0,1,1]
	v_pk_fma_f32 v[108:109], v[72:73], v[166:167], v[108:109] op_sel_hi:[0,1,1]
	v_pk_fma_f32 v[110:111], v[72:73], v[168:169], v[110:111] op_sel_hi:[0,1,1]
	v_pk_fma_f32 v[112:113], v[72:73], v[170:171], v[112:113] op_sel_hi:[0,1,1]
	v_pk_fma_f32 v[106:107], v[74:75], v[172:173], v[106:107] op_sel_hi:[0,1,1]
	v_pk_fma_f32 v[108:109], v[74:75], v[174:175], v[108:109] op_sel_hi:[0,1,1]
	v_pk_fma_f32 v[110:111], v[74:75], v[176:177], v[110:111] op_sel_hi:[0,1,1]
	v_pk_fma_f32 v[112:113], v[74:75], v[178:179], v[112:113] op_sel_hi:[0,1,1]
	v_pk_fma_f32 v[106:107], v[76:77], v[180:181], v[106:107] op_sel_hi:[0,1,1]
	v_pk_fma_f32 v[108:109], v[76:77], v[182:183], v[108:109] op_sel_hi:[0,1,1]
	v_pk_fma_f32 v[110:111], v[76:77], v[184:185], v[110:111] op_sel_hi:[0,1,1]
; __device__ __forceinline__ void phase_mix(KA a, int l, LAS unsigned char* lds, int vcu, int G, int wave) {
;     ...
;                 for (int ck = 0; ck < 33; ++ck) { const float* p = pb + (size_t)ck * 16 * 132; const float w = __builtin_amdgcn_exp2f(p[0] - M); L += p[1] * w;
;                     const f32x4 o0 = *(const f32x4*)(p + 4 + d0), o1 = *(const f32x4*)(p + 8 + d0);
;                     o[0] += o0.x * w; o[1] += o0.y * w; o[2] += o0.z * w; o[3] += o0.w * w; o[4] += o1.x * w; o[5] += o1.y * w; o[6] += o1.z * w; o[7] += o1.w * w; }
	v_pk_fma_f32 v[112:113], v[76:77], v[186:187], v[112:113] op_sel_hi:[0,1,1]
	v_pk_fma_f32 v[106:107], v[78:79], v[208:209], v[106:107] op_sel_hi:[0,1,1]
	v_pk_fma_f32 v[108:109], v[78:79], v[210:211], v[108:109] op_sel_hi:[0,1,1]
	v_pk_fma_f32 v[110:111], v[78:79], v[212:213], v[110:111] op_sel_hi:[0,1,1]
	v_pk_fma_f32 v[112:113], v[78:79], v[214:215], v[112:113] op_sel_hi:[0,1,1]
	v_pk_fma_f32 v[106:107], v[80:81], v[216:217], v[106:107] op_sel_hi:[0,1,1]
	v_pk_fma_f32 v[108:109], v[80:81], v[218:219], v[108:109] op_sel_hi:[0,1,1]
	v_pk_fma_f32 v[110:111], v[80:81], v[220:221], v[110:111] op_sel_hi:[0,1,1]
	v_pk_fma_f32 v[112:113], v[80:81], v[222:223], v[112:113] op_sel_hi:[0,1,1]
	v_pk_fma_f32 v[106:107], v[82:83], v[224:225], v[106:107] op_sel_hi:[0,1,1]
	v_pk_fma_f32 v[108:109], v[82:83], v[226:227], v[108:109] op_sel_hi:[0,1,1]
	v_pk_fma_f32 v[110:111], v[82:83], v[228:229], v[110:111] op_sel_hi:[0,1,1]
	v_pk_fma_f32 v[112:113], v[82:83], v[230:231], v[112:113] op_sel_hi:[0,1,1]
	s_nop 1
	global_load_dwordx4 v[114:117], v153, s[20:21] offset:16
	global_load_dwordx4 v[118:121], v153, s[20:21] offset:32
	s_add_u32 s20, s20, 0x2100
	s_addc_u32 s21, s21, 0
	global_load_dwordx4 v[122:125], v153, s[20:21] offset:16
	global_load_dwordx4 v[126:129], v153, s[20:21] offset:32
	s_add_u32 s20, s20, 0x2100
	s_addc_u32 s21, s21, 0
	global_load_dwordx4 v[130:133], v153, s[20:21] offset:16
	global_load_dwordx4 v[134:137], v153, s[20:21] offset:32
	s_add_u32 s20, s20, 0x2100
	s_addc_u32 s21, s21, 0
	global_load_dwordx4 v[138:141], v153, s[20:21] offset:16
	global_load_dwordx4 v[142:145], v153, s[20:21] offset:32
	s_add_u32 s20, s20, 0x2100
	s_addc_u32 s21, s21, 0
	global_load_dwordx4 v[156:159], v153, s[20:21] offset:16
	global_load_dwordx4 v[160:163], v153, s[20:21] offset:32
	s_add_u32 s20, s20, 0x2100
	s_addc_u32 s21, s21, 0
	global_load_dwordx4 v[164:167], v153, s[20:21] offset:16
	global_load_dwordx4 v[168:171], v153, s[20:21] offset:32
	s_add_u32 s20, s20, 0x2100
	s_addc_u32 s21, s21, 0
	global_load_dwordx4 v[172:175], v153, s[20:21] offset:16
	global_load_dwordx4 v[176:179], v153, s[20:21] offset:32
	s_add_u32 s20, s20, 0x2100
	s_addc_u32 s21, s21, 0
	global_load_dwordx4 v[180:183], v153, s[20:21] offset:16
	global_load_dwordx4 v[184:187], v153, s[20:21] offset:32
	s_add_u32 s20, s20, 0x2100
	s_addc_u32 s21, s21, 0
	global_load_dwordx4 v[208:211], v153, s[20:21] offset:16
	global_load_dwordx4 v[212:215], v153, s[20:21] offset:32
	s_add_u32 s20, s20, 0x2100
	s_addc_u32 s21, s21, 0
	global_load_dwordx4 v[216:219], v153, s[20:21] offset:16
	global_load_dwordx4 v[220:223], v153, s[20:21] offset:32
	s_add_u32 s20, s20, 0x2100
	s_addc_u32 s21, s21, 0
	global_load_dwordx4 v[224:227], v153, s[20:21] offset:16
	global_load_dwordx4 v[228:231], v153, s[20:21] offset:32
	s_waitcnt vmcnt(0)
; __device__ __forceinline__ unsigned pk2(float lo, float hi) { return pg8::cvt_pk_bf16(lo, hi); }
; __device__ __forceinline__ float bf2f(unsigned short u) { return __uint_as_float((unsigned)u << 16); }
; __device__ __forceinline__ void phase_mix(KA a, int l, LAS unsigned char* lds, int vcu, int G, int wave) {
;     ...
;                 for (int ck = 0; ck < 33; ++ck) { const float* p = pb + (size_t)ck * 16 * 132; const float w = __builtin_amdgcn_exp2f(p[0] - M); L += p[1] * w;
;                     const f32x4 o0 = *(const f32x4*)(p + 4 + d0), o1 = *(const f32x4*)(p + 8 + d0);
;                     o[0] += o0.x * w; o[1] += o0.y * w; o[2] += o0.z * w; o[3] += o0.w * w; o[4] += o1.x * w; o[5] += o1.y * w; o[6] += o1.z * w; o[7] += o1.w * w; }
;                 const float il = 1.0f / L;
; #pragma unroll
;                 for (int e = 0; e < 8; ++e) v[j * 8 + e] = bf2f((unsigned short)(pk2(o[e] * il, 0.f) & 0xffffu));
;             }
	v_pk_fma_f32 v[106:107], v[84:85], v[114:115], v[106:107] op_sel_hi:[0,1,1]
	v_pk_fma_f32 v[108:109], v[84:85], v[116:117], v[108:109] op_sel_hi:[0,1,1]
	v_pk_fma_f32 v[110:111], v[84:85], v[118:119], v[110:111] op_sel_hi:[0,1,1]
	v_pk_fma_f32 v[112:113], v[84:85], v[120:121], v[112:113] op_sel_hi:[0,1,1]
	v_pk_fma_f32 v[106:107], v[86:87], v[122:123], v[106:107] op_sel_hi:[0,1,1]
	v_pk_fma_f32 v[108:109], v[86:87], v[124:125], v[108:109] op_sel_hi:[0,1,1]
	v_pk_fma_f32 v[110:111], v[86:87], v[126:127], v[110:111] op_sel_hi:[0,1,1]
	v_pk_fma_f32 v[112:113], v[86:87], v[128:129], v[112:113] op_sel_hi:[0,1,1]
	v_pk_fma_f32 v[106:107], v[88:89], v[130:131], v[106:107] op_sel_hi:[0,1,1]
	v_pk_fma_f32 v[108:109], v[88:89], v[132:133], v[108:109] op_sel_hi:[0,1,1]
	v_pk_fma_f32 v[110:111], v[88:89], v[134:135], v[110:111] op_sel_hi:[0,1,1]
	v_pk_fma_f32 v[112:113], v[88:89], v[136:137], v[112:113] op_sel_hi:[0,1,1]
	v_pk_fma_f32 v[106:107], v[90:91], v[138:139], v[106:107] op_sel_hi:[0,1,1]
	v_pk_fma_f32 v[108:109], v[90:91], v[140:141], v[108:109] op_sel_hi:[0,1,1]
	v_pk_fma_f32 v[110:111], v[90:91], v[142:143], v[110:111] op_sel_hi:[0,1,1]
	v_pk_fma_f32 v[112:113], v[90:91], v[144:145], v[112:113] op_sel_hi:[0,1,1]
	v_pk_fma_f32 v[106:107], v[92:93], v[156:157], v[106:107] op_sel_hi:[0,1,1]
	v_pk_fma_f32 v[108:109], v[92:93], v[158:159], v[108:109] op_sel_hi:[0,1,1]
	v_pk_fma_f32 v[110:111], v[92:93], v[160:161], v[110:111] op_sel_hi:[0,1,1]
	v_pk_fma_f32 v[112:113], v[92:93], v[162:163], v[112:113] op_sel_hi:[0,1,1]
	v_pk_fma_f32 v[106:107], v[94:95], v[164:165], v[106:107] op_sel_hi:[0,1,1]
	v_pk_fma_f32 v[108:109], v[94:95], v[166:167], v[108:109] op_sel_hi:[0,1,1]
	v_pk_fma_f32 v[110:111], v[94:95], v[168:169], v[110:111] op_sel_hi:[0,1,1]
	v_pk_fma_f32 v[112:113], v[94:95], v[170:171], v[112:113] op_sel_hi:[0,1,1]
	v_pk_fma_f32 v[106:107], v[96:97], v[172:173], v[106:107] op_sel_hi:[0,1,1]
	v_pk_fma_f32 v[108:109], v[96:97], v[174:175], v[108:109] op_sel_hi:[0,1,1]
	v_pk_fma_f32 v[110:111], v[96:97], v[176:177], v[110:111] op_sel_hi:[0,1,1]
	v_pk_fma_f32 v[112:113], v[96:97], v[178:179], v[112:113] op_sel_hi:[0,1,1]
	v_pk_fma_f32 v[106:107], v[98:99], v[180:181], v[106:107] op_sel_hi:[0,1,1]
	v_pk_fma_f32 v[108:109], v[98:99], v[182:183], v[108:109] op_sel_hi:[0,1,1]
	v_pk_fma_f32 v[110:111], v[98:99], v[184:185], v[110:111] op_sel_hi:[0,1,1]
	v_pk_fma_f32 v[112:113], v[98:99], v[186:187], v[112:113] op_sel_hi:[0,1,1]
	v_pk_fma_f32 v[106:107], v[100:101], v[208:209], v[106:107] op_sel_hi:[0,1,1]
	v_pk_fma_f32 v[108:109], v[100:101], v[210:211], v[108:109] op_sel_hi:[0,1,1]
	v_pk_fma_f32 v[110:111], v[100:101], v[212:213], v[110:111] op_sel_hi:[0,1,1]
	v_pk_fma_f32 v[112:113], v[100:101], v[214:215], v[112:113] op_sel_hi:[0,1,1]
	v_pk_fma_f32 v[106:107], v[102:103], v[216:217], v[106:107] op_sel_hi:[0,1,1]
	v_pk_fma_f32 v[108:109], v[102:103], v[218:219], v[108:109] op_sel_hi:[0,1,1]
	v_pk_fma_f32 v[110:111], v[102:103], v[220:221], v[110:111] op_sel_hi:[0,1,1]
	v_pk_fma_f32 v[112:113], v[102:103], v[222:223], v[112:113] op_sel_hi:[0,1,1]
	v_pk_fma_f32 v[106:107], v[104:105], v[224:225], v[106:107] op_sel_hi:[0,1,1]
	v_pk_fma_f32 v[108:109], v[104:105], v[226:227], v[108:109] op_sel_hi:[0,1,1]
	v_pk_fma_f32 v[110:111], v[104:105], v[228:229], v[110:111] op_sel_hi:[0,1,1]
	v_pk_fma_f32 v[112:113], v[104:105], v[230:231], v[112:113] op_sel_hi:[0,1,1]
	v_div_scale_f32 v194, s[18:19], v195, v195, 1.0
	v_rcp_f32_e32 v197, v194
	s_nop 0
	v_fma_f32 v40, -v194, v197, 1.0
	v_fmac_f32_e32 v197, v40, v197
	v_div_scale_f32 v40, vcc, 1.0, v195, 1.0
	v_mul_f32_e32 v41, v40, v197
	v_fma_f32 v42, -v194, v41, v40
	v_fmac_f32_e32 v41, v42, v197
	v_fma_f32 v194, -v194, v41, v40
	v_div_fmas_f32 v194, v194, v197, v41
	v_div_fixup_f32 v194, v194, v195, 1.0
	v_mul_f32_e32 v40, v194, v106
	v_mul_f32_e32 v41, v194, v107
	v_cvt_pk_bf16_f32 v4, v40, v149
	v_cvt_pk_bf16_f32 v24, v41, v149
	s_nop 0
	v_lshlrev_b32_e32 v24, 16, v24
	v_mul_f32_e32 v40, v194, v108
	v_mul_f32_e32 v41, v194, v109
	v_cvt_pk_bf16_f32 v5, v40, v149
	v_cvt_pk_bf16_f32 v22, v41, v149
	s_nop 0
	v_lshlrev_b32_e32 v22, 16, v22
	v_mul_f32_e32 v40, v194, v110
	v_mul_f32_e32 v41, v194, v111
	v_cvt_pk_bf16_f32 v6, v40, v149
	v_cvt_pk_bf16_f32 v20, v41, v149
	s_nop 0
	v_lshlrev_b32_e32 v20, 16, v20
	v_mul_f32_e32 v40, v194, v112
	v_mul_f32_e32 v41, v194, v113
	v_cvt_pk_bf16_f32 v7, v40, v149
	v_cvt_pk_bf16_f32 v18, v41, v149
	s_nop 0
	v_lshlrev_b32_e32 v18, 16, v18
	s_mov_b64 s[22:23], 0
	s_mov_b32 s26, 0x17601000
	s_mov_b32 s54, 0x800000

; __device__ __forceinline__ u32x4_h zero4u() { unsigned z = 0u; asm volatile("" : "+v"(z)); return (u32x4_h){z, z, z, z}; }
; #define LAS __attribute__((address_space(3)))
; __device__ __forceinline__ unsigned pk2(float lo, float hi) { return pg8::cvt_pk_bf16(lo, hi); }
; __device__ __forceinline__ void phase_mix(KA a, int l, LAS unsigned char* lds, int vcu, int G, int wave) {
;     ...
;     constexpr int RS = 1032;
;     LAS bf16* tile = (LAS bf16*)lds;
;     const bf16* YT = (const bf16*)(a->ws + WS_YT);
;     for (int tl = vcu; tl < (T_ + 31) / 32; tl += G) {
;         const int t0 = tl * 32;
;         __syncthreads();
; #pragma unroll 2
;         for (int p = 0; p < 8; ++p) {
;             const int c = p * 128 + (tid >> 2), tk = (tid & 3) * 8;
;             u32x4 x = zero4u();
;             if (t0 + tk < T_) x = *(const u32x4*)(YT + (size_t)c * TP + t0 + tk);
;     ...
;             for (int j = 0; j < 2; ++j) { const float* g = gy + j * 512 + lane * 8; u32x4 w;
;                 w.x = pk2(v[j * 8 + 0] * rs * g[0], v[j * 8 + 1] * rs * g[1]); w.y = pk2(v[j * 8 + 2] * rs * g[2], v[j * 8 + 3] * rs * g[3]);
;                 w.z = pk2(v[j * 8 + 4] * rs * g[4], v[j * 8 + 5] * rs * g[5]); w.w = pk2(v[j * 8 + 6] * rs * g[6], v[j * 8 + 7] * rs * g[7]);
.LBB0_142:
	s_cmpk_gt_i32 s11, 0x100
	s_cbranch_scc1 .LBB0_158
	s_xor_b32 s11, s11, 0x80
	v_readlane_b32 s0, v253, 25
	s_lshl_b64 s[18:19], s[42:43], 2
	s_waitcnt lgkmcnt(0)
	s_add_u32 s18, s48, s18
	v_or_b32_e32 v0, s0, v27
	s_addc_u32 s19, s49, s19
	v_ashrrev_i32_e32 v2, 2, v0
	v_lshlrev_b32_e32 v0, 3, v26
	v_mov_b32_e32 v9, v149
	s_movk_i32 s0, 0x4200
	v_and_b32_e32 v16, 24, v0
	v_lshl_add_u64 v[4:5], s[18:19], 0, v[148:149]
	v_lshl_add_u64 v[6:7], s[40:41], 0, v[8:9]
	v_mad_i64_i32 v[0:1], s[18:19], v2, s0, 0
	v_and_b32_e32 v9, 3, v26
	v_lshl_or_b32 v0, v9, 4, v0
	v_lshl_add_u64 v[0:1], s[16:17], 0, v[0:1]
	s_mov_b64 s[18:19], 0x1fe20000
	s_lshl_b32 s42, s11, 5
	v_readlane_b32 s0, v253, 11
	v_mul_u32_u24_e32 v3, 0x810, v16
	v_lshl_add_u64 v[10:11], v[0:1], 0, s[18:19]
	v_lshlrev_b32_e32 v0, 1, v2
	s_add_i32 s7, s0, s42
	v_readlane_b32 s0, v254, 42
	s_lshl_b32 s5, s15, 5
	v_add3_u32 v17, v3, v0, 0
	v_add_u32_e32 v18, s0, v8
	s_mov_b32 s9, s11
	v_readlane_b32 s1, v253, 26
	global_load_dwordx2 v[232:233], v[4:5], off
	global_load_dwordx2 v[234:235], v[4:5], off offset:8
	global_load_dwordx2 v[236:237], v[4:5], off offset:16
	global_load_dwordx2 v[238:239], v[4:5], off offset:24
	global_load_dwordx2 v[240:241], v[4:5], off offset:2048
	global_load_dwordx2 v[242:243], v[4:5], off offset:2056
	global_load_dwordx2 v[244:245], v[4:5], off offset:2064
	global_load_dwordx2 v[246:247], v[4:5], off offset:2072
	s_branch .LBB0_145

; __device__ __forceinline__ u32x4_h zero4u() { unsigned z = 0u; asm volatile("" : "+v"(z)); return (u32x4_h){z, z, z, z}; }
; __device__ __forceinline__ void phase_mix(KA a, int l, LAS unsigned char* lds, int vcu, int G, int wave) {
;     ...
;         __syncthreads();
; #pragma unroll 2
;         for (int p = 0; p < 8; ++p) {
;             const int c = p * 128 + (tid >> 2), tk = (tid & 3) * 8;
;             u32x4 x = zero4u();
;             if (t0 + tk < T_) x = *(const u32x4*)(YT + (size_t)c * TP + t0 + tk);
;             tile[(tk + 0) * RS + c] = (bf16)(x.x & 0xffffu); tile[(tk + 1) * RS + c] = (bf16)(x.x >> 16);
;             tile[(tk + 2) * RS + c] = (bf16)(x.y & 0xffffu); tile[(tk + 3) * RS + c] = (bf16)(x.y >> 16);
;             tile[(tk + 4) * RS + c] = (bf16)(x.z & 0xffffu); tile[(tk + 5) * RS + c] = (bf16)(x.z >> 16);
;             tile[(tk + 6) * RS + c] = (bf16)(x.w & 0xffffu); tile[(tk + 7) * RS + c] = (bf16)(x.w >> 16);
;         }
;         __syncthreads();
.LBB0_145:
	s_ashr_i32 s43, s42, 31
	v_lshl_or_b32 v0, s9, 5, v16
	v_lshl_add_u64 v[8:9], s[42:43], 1, v[10:11]
	v_cmp_gt_i32_e64 s[40:41], s85, v0
	s_mov_b32 s11, 0
	s_waitcnt vmcnt(0)
	s_barrier
	v_mov_b32_e32 v40, 0
	v_mov_b32_e32 v41, 0
	v_mov_b32_e32 v42, 0
	v_mov_b32_e32 v43, 0
	v_mov_b32_e32 v44, 0
	v_mov_b32_e32 v45, 0
	v_mov_b32_e32 v46, 0
	v_mov_b32_e32 v47, 0
	v_mov_b32_e32 v48, 0
	v_mov_b32_e32 v49, 0
	v_mov_b32_e32 v50, 0
	v_mov_b32_e32 v51, 0
	v_mov_b32_e32 v52, 0
	v_mov_b32_e32 v53, 0
	v_mov_b32_e32 v54, 0
	v_mov_b32_e32 v55, 0
	v_mov_b32_e32 v56, 0
	v_mov_b32_e32 v57, 0
	v_mov_b32_e32 v58, 0
	v_mov_b32_e32 v59, 0
	v_mov_b32_e32 v60, 0
	v_mov_b32_e32 v61, 0
	v_mov_b32_e32 v62, 0
	v_mov_b32_e32 v63, 0
	v_mov_b32_e32 v64, 0
	v_mov_b32_e32 v65, 0
	v_mov_b32_e32 v66, 0
	v_mov_b32_e32 v67, 0
	v_mov_b32_e32 v68, 0
	v_mov_b32_e32 v69, 0
	v_mov_b32_e32 v70, 0
	v_mov_b32_e32 v71, 0
	s_mov_b64 s[18:19], 0x210000
	s_and_saveexec_b64 s[22:23], s[40:41]
	s_cbranch_execz .Lmix_tile_noload
	v_add_co_u32_e32 v72, vcc, 0xffdf0000, v8
	s_nop 1
	v_addc_co_u32_e32 v73, vcc, -1, v9, vcc
	global_load_dwordx4 v[40:43], v[72:73], off
	v_lshl_add_u64 v[72:73], v[72:73], 0, s[18:19]
	global_load_dwordx4 v[44:47], v[72:73], off
	v_lshl_add_u64 v[72:73], v[72:73], 0, s[18:19]
	global_load_dwordx4 v[48:51], v[72:73], off
	v_lshl_add_u64 v[72:73], v[72:73], 0, s[18:19]
	global_load_dwordx4 v[52:55], v[72:73], off
	v_lshl_add_u64 v[72:73], v[72:73], 0, s[18:19]
	global_load_dwordx4 v[56:59], v[72:73], off
	v_lshl_add_u64 v[72:73], v[72:73], 0, s[18:19]
	global_load_dwordx4 v[60:63], v[72:73], off
	v_lshl_add_u64 v[72:73], v[72:73], 0, s[18:19]
	global_load_dwordx4 v[64:67], v[72:73], off
	v_lshl_add_u64 v[72:73], v[72:73], 0, s[18:19]
	global_load_dwordx4 v[68:71], v[72:73], off
.Lmix_tile_noload:
	s_or_b64 exec, exec, s[22:23]
	s_waitcnt vmcnt(0)
	ds_write_b16 v17, v40 offset:0
	ds_write_b16_d16_hi v17, v40 offset:2064
	ds_write_b16 v17, v41 offset:4128
	ds_write_b16_d16_hi v17, v41 offset:6192
	ds_write_b16 v17, v42 offset:8256
	ds_write_b16_d16_hi v17, v42 offset:10320
	ds_write_b16 v17, v43 offset:12384
	ds_write_b16_d16_hi v17, v43 offset:14448
	ds_write_b16 v17, v44 offset:256
	ds_write_b16_d16_hi v17, v44 offset:2320
	ds_write_b16 v17, v45 offset:4384
	ds_write_b16_d16_hi v17, v45 offset:6448
	ds_write_b16 v17, v46 offset:8512
	ds_write_b16_d16_hi v17, v46 offset:10576
	ds_write_b16 v17, v47 offset:12640
	ds_write_b16_d16_hi v17, v47 offset:14704
	ds_write_b16 v17, v48 offset:512
	ds_write_b16_d16_hi v17, v48 offset:2576
	ds_write_b16 v17, v49 offset:4640
	ds_write_b16_d16_hi v17, v49 offset:6704
	ds_write_b16 v17, v50 offset:8768
	ds_write_b16_d16_hi v17, v50 offset:10832
	ds_write_b16 v17, v51 offset:12896
	ds_write_b16_d16_hi v17, v51 offset:14960
	ds_write_b16 v17, v52 offset:768
	ds_write_b16_d16_hi v17, v52 offset:2832
	ds_write_b16 v17, v53 offset:4896
	ds_write_b16_d16_hi v17, v53 offset:6960
	ds_write_b16 v17, v54 offset:9024
	ds_write_b16_d16_hi v17, v54 offset:11088
	ds_write_b16 v17, v55 offset:13152
	ds_write_b16_d16_hi v17, v55 offset:15216
	ds_write_b16 v17, v56 offset:1024
	ds_write_b16_d16_hi v17, v56 offset:3088
	ds_write_b16 v17, v57 offset:5152
	ds_write_b16_d16_hi v17, v57 offset:7216
	ds_write_b16 v17, v58 offset:9280
	ds_write_b16_d16_hi v17, v58 offset:11344
	ds_write_b16 v17, v59 offset:13408
	ds_write_b16_d16_hi v17, v59 offset:15472
	ds_write_b16 v17, v60 offset:1280
	ds_write_b16_d16_hi v17, v60 offset:3344
	ds_write_b16 v17, v61 offset:5408
	ds_write_b16_d16_hi v17, v61 offset:7472
	ds_write_b16 v17, v62 offset:9536
	ds_write_b16_d16_hi v17, v62 offset:11600
	ds_write_b16 v17, v63 offset:13664
	ds_write_b16_d16_hi v17, v63 offset:15728
	ds_write_b16 v17, v64 offset:1536
	ds_write_b16_d16_hi v17, v64 offset:3600
	ds_write_b16 v17, v65 offset:5664
	ds_write_b16_d16_hi v17, v65 offset:7728
	ds_write_b16 v17, v66 offset:9792
	ds_write_b16_d16_hi v17, v66 offset:11856
	ds_write_b16 v17, v67 offset:13920
	ds_write_b16_d16_hi v17, v67 offset:15984
	ds_write_b16 v17, v68 offset:1792
	ds_write_b16_d16_hi v17, v68 offset:3856
	ds_write_b16 v17, v69 offset:5920
	ds_write_b16_d16_hi v17, v69 offset:7984
	ds_write_b16 v17, v70 offset:10048
	ds_write_b16_d16_hi v17, v70 offset:12112
	ds_write_b16 v17, v71 offset:14176
	ds_write_b16_d16_hi v17, v71 offset:16240

; #define LAS __attribute__((address_space(3)))
; __device__ __forceinline__ unsigned pk2(float lo, float hi) { return pg8::cvt_pk_bf16(lo, hi); }
; __device__ __forceinline__ float bflo(unsigned w) { return __uint_as_float(w << 16); }
; __device__ __forceinline__ float bfhi(unsigned w) { return __uint_as_float(w & 0xffff0000u); }
; __device__ __forceinline__ void phase_mix(KA a, int l, LAS unsigned char* lds, int vcu, int G, int wave) {
;     ...
;         for (int r = 0; r < 4; ++r) {
;             const int tr = wave * 4 + r, t = t0 + tr;
;             u32x4 x[2]; x[0] = *(const LAS u32x4*)(tile + tr * RS + lane * 8); x[1] = *(const LAS u32x4*)(tile + tr * RS + 512 + lane * 8);
;             float v[16]; float ss = 0.f;
; #pragma unroll
;             for (int j = 0; j < 2; ++j) { v[j * 8 + 0] = bflo(x[j].x); v[j * 8 + 1] = bfhi(x[j].x); v[j * 8 + 2] = bflo(x[j].y); v[j * 8 + 3] = bfhi(x[j].y);
;                 v[j * 8 + 4] = bflo(x[j].z); v[j * 8 + 5] = bfhi(x[j].z); v[j * 8 + 6] = bflo(x[j].w); v[j * 8 + 7] = bfhi(x[j].w); }
; #pragma unroll
;             for (int e = 0; e < 16; ++e) ss += v[e] * v[e];
;             const float rs = rsqrtf(wave_sum(ss) * (1.0f / 1024) + EPS);
; #pragma unroll
;             for (int j = 0; j < 2; ++j) { const float* g = gy + j * 512 + lane * 8; u32x4 w;
;                 w.x = pk2(v[j * 8 + 0] * rs * g[0], v[j * 8 + 1] * rs * g[1]); w.y = pk2(v[j * 8 + 2] * rs * g[2], v[j * 8 + 3] * rs * g[3]);
;                 w.z = pk2(v[j * 8 + 4] * rs * g[4], v[j * 8 + 5] * rs * g[5]); w.w = pk2(v[j * 8 + 6] * rs * g[6], v[j * 8 + 7] * rs * g[7]);
;                 if (t < T_) *(u32x4*)(MIX + (size_t)t * 2048 + 1024 + j * 512 + lane * 8) = w; }
.LBB0_153:
	v_add_u32_e32 v8, s11, v18
	ds_read_b128 v[0:3], v8
	ds_read_b128 v[12:15], v8 offset:1024
	s_cmpk_lt_i32 s40, 0x2010
	s_cselect_b64 s[22:23], -1, 0
	s_ashr_i32 s41, s40, 31
	s_waitcnt lgkmcnt(1)
	v_and_b32_e32 v33, 0xffff0000, v0
	v_lshlrev_b32_e32 v32, 16, v0
	v_lshlrev_b32_e32 v36, 16, v2
	v_and_b32_e32 v37, 0xffff0000, v2
	v_mul_f32_e32 v2, v33, v33
	v_lshlrev_b32_e32 v34, 16, v1
	v_fmac_f32_e32 v2, v32, v32
	v_and_b32_e32 v35, 0xffff0000, v1
	v_fmac_f32_e32 v2, v34, v34
	v_fmac_f32_e32 v2, v35, v35
	v_fmac_f32_e32 v2, v36, v36
	v_lshlrev_b32_e32 v38, 16, v3
	v_fmac_f32_e32 v2, v37, v37
	v_and_b32_e32 v39, 0xffff0000, v3
	v_fmac_f32_e32 v2, v38, v38
	s_waitcnt lgkmcnt(0)
	v_lshlrev_b32_e32 v28, 16, v12
	v_fmac_f32_e32 v2, v39, v39
	v_and_b32_e32 v27, 0xffff0000, v12
	v_fmac_f32_e32 v2, v28, v28
	v_lshlrev_b32_e32 v26, 16, v13
	v_fmac_f32_e32 v2, v27, v27
	v_and_b32_e32 v25, 0xffff0000, v13
	v_fmac_f32_e32 v2, v26, v26
	v_and_b32_e32 v12, 0xffff0000, v14
	v_lshlrev_b32_e32 v13, 16, v14
	v_fmac_f32_e32 v2, v25, v25
	v_pk_mul_f32 v[0:1], v[12:13], v[12:13]
	v_and_b32_e32 v8, 0xffff0000, v15
	v_add_f32_e32 v1, v1, v2
	v_lshlrev_b32_e32 v9, 16, v15
	v_add_f32_e32 v2, v0, v1
	v_pk_mul_f32 v[0:1], v[8:9], v[8:9]
	s_lshl_b64 s[18:19], s[40:41], 12
	v_add_f32_e32 v1, v1, v2
	v_add_f32_e32 v0, v0, v1
	ds_bpermute_b32 v1, v19, v0
	s_cmpk_gt_i32 s40, 0x200f
	s_waitcnt lgkmcnt(0)
	v_add_f32_e32 v0, v0, v1
	ds_bpermute_b32 v1, v20, v0
	s_waitcnt lgkmcnt(0)
	v_add_f32_e32 v0, v0, v1
	ds_bpermute_b32 v1, v21, v0
	s_waitcnt lgkmcnt(0)
	v_add_f32_e32 v0, v0, v1
	ds_bpermute_b32 v1, v22, v0
	s_waitcnt lgkmcnt(0)
	v_add_f32_e32 v0, v0, v1
	ds_bpermute_b32 v1, v23, v0
	s_waitcnt lgkmcnt(0)
	v_add_f32_e32 v0, v0, v1
	ds_bpermute_b32 v1, v24, v0
	s_waitcnt lgkmcnt(0)
	v_add_f32_e32 v0, v0, v1
	v_fmamk_f32 v0, v0, 0x3a800000, v154
	v_mul_f32_e32 v1, 0x4b800000, v0
	v_cmp_gt_f32_e32 vcc, s54, v0
	s_nop 1
	v_cndmask_b32_e32 v0, v0, v1, vcc
	v_rsq_f32_e32 v0, v0
	s_nop 0
	v_mul_f32_e32 v1, 0x45800000, v0
	v_cndmask_b32_e32 v29, v0, v1, vcc
	v_mul_f32_e32 v0, v29, v32
	v_mul_f32_e32 v1, v29, v33
	v_mul_f32_e32 v0, v232, v0
	v_mul_f32_e32 v1, v233, v1
	v_cvt_pk_bf16_f32 v0, v0, v1
	v_mul_f32_e32 v1, v29, v34
	v_mul_f32_e32 v14, v29, v35
	v_mul_f32_e32 v15, v29, v37
	v_mul_f32_e32 v32, v29, v39
	v_mul_f32_e32 v1, v234, v1
	v_mul_f32_e32 v2, v235, v14
	v_cvt_pk_bf16_f32 v1, v1, v2
	v_mul_f32_e32 v14, v29, v36
	v_mul_f32_e32 v2, v236, v14
	v_mul_f32_e32 v3, v237, v15
	v_cvt_pk_bf16_f32 v2, v2, v3
	v_mul_f32_e32 v3, v29, v38
	v_lshl_add_u64 v[14:15], v[6:7], 0, s[18:19]
	v_mul_f32_e32 v3, v238, v3
	v_mul_f32_e32 v30, v239, v32
	v_cvt_pk_bf16_f32 v3, v3, v30
	s_cbranch_scc1 .LBB0_155
	global_store_dwordx4 v[14:15], v[0:3], off offset:2048
	s_nop 1
.LBB0_155:
	s_nop 0
	v_mul_f32_e32 v2, v29, v28
	v_mul_f32_e32 v3, v29, v27
	v_mul_f32_e32 v25, v29, v25
	v_mul_f32_e32 v13, v29, v13
	v_mul_f32_e32 v12, v29, v12
	v_mul_f32_e32 v8, v29, v8
	s_andn2_b64 vcc, exec, s[22:23]
	v_mul_f32_e32 v0, v2, v240
	v_mul_f32_e32 v1, v3, v241
	v_cvt_pk_bf16_f32 v0, v0, v1
	v_mul_f32_e32 v1, v29, v26
	v_mul_f32_e32 v1, v1, v242
	v_mul_f32_e32 v2, v25, v243
	v_cvt_pk_bf16_f32 v1, v1, v2
	v_mul_f32_e32 v2, v13, v244
	v_mul_f32_e32 v3, v12, v245
	v_cvt_pk_bf16_f32 v2, v2, v3
	v_mul_f32_e32 v3, v29, v9
	v_mul_f32_e32 v3, v3, v246
	v_mul_f32_e32 v8, v8, v247
	v_cvt_pk_bf16_f32 v3, v3, v8
	s_cbranch_vccnz .LBB0_152
	global_store_dwordx4 v[14:15], v[0:3], off offset:3072
	s_nop 1
	s_branch .LBB0_152
